# v34 + P7/P9 epilogue trims (fold rstd mov into fmamk, drop dead rssp address calc)
# baseline (speedup 1.0000x reference)
.LBB0_1467:
	v_lshl_add_u32 v138, s28, 8, v140
	v_ashrrev_i32_e32 v139, 31, v138
	v_lshlrev_b64 v[176:177], 6, v[138:139]
	v_lshl_add_u64 v[176:177], s[8:9], 0, v[176:177]
	v_and_b32_e32 v178, 48, v188
	v_mov_b32_e32 v179, 0
	s_mov_b64 s[98:99], 0x2000
	v_lshl_add_u64 v[176:177], v[176:177], 0, v[178:179]
	v_lshl_add_u64 v[178:179], v[176:177], 0, s[98:99]
	global_load_dwordx4 v[180:183], v[176:177], off
	global_load_dwordx4 v[184:187], v[176:177], off offset:1024
	global_load_dwordx4 v[192:195], v[176:177], off offset:2048
	global_load_dwordx4 v[196:199], v[176:177], off offset:3072
	global_load_dwordx4 v[200:203], v[178:179], off
	global_load_dwordx4 v[204:207], v[178:179], off offset:1024
	global_load_dwordx4 v[208:211], v[178:179], off offset:2048
	global_load_dwordx4 v[212:215], v[178:179], off offset:3072
	v_and_b32_e32 v174, 15, v188
	v_lshlrev_b32_e32 v216, 2, v174
	v_add_u32_e32 v217, 64, v216
	v_add_u32_e32 v218, 128, v216
	v_add_u32_e32 v219, 192, v216
	v_lshlrev_b64 v[148:149], 6, v[138:139]
	v_lshl_add_u64 v[160:161], s[8:9], 0, v[148:149]
	v_lshl_or_b32 v164, s26, 7, v142
	v_ashrrev_i32_e32 v165, 31, v164
	v_pk_mul_f32 v[166:167], v[122:123], v[114:115]
	v_lshlrev_b64 v[122:123], 1, v[164:165]
	v_pk_mul_f32 v[126:127], v[126:127], v[118:119]
	v_pk_mul_f32 v[124:125], v[124:125], v[116:117]
	v_pk_mul_f32 v[168:169], v[120:121], v[112:113]
	v_mov_b64_e32 v[120:121], s[10:11]
	v_or_b32_e32 v172, 16, v138
	v_mad_i64_i32 v[170:171], s[4:5], v138, s55, v[120:121]
	v_ashrrev_i32_e32 v173, 31, v172
	v_pk_mul_f32 v[110:111], v[110:111], v[102:103]
	v_pk_mul_f32 v[108:109], v[108:109], v[100:101]
	v_pk_mul_f32 v[106:107], v[106:107], v[98:99]
	v_pk_mul_f32 v[104:105], v[104:105], v[96:97]
	v_pk_mul_f32 v[94:95], v[94:95], v[86:87]
	v_pk_mul_f32 v[92:93], v[92:93], v[84:85]
	v_pk_mul_f32 v[90:91], v[90:91], v[82:83]
	v_pk_mul_f32 v[88:89], v[88:89], v[80:81]
	v_pk_mul_f32 v[78:79], v[78:79], v[70:71]
	v_pk_mul_f32 v[76:77], v[76:77], v[68:69]
	v_pk_mul_f32 v[74:75], v[74:75], v[66:67]
	v_pk_mul_f32 v[72:73], v[72:73], v[64:65]
	v_pk_mul_f32 v[62:63], v[62:63], v[54:55]
	v_pk_mul_f32 v[60:61], v[60:61], v[52:53]
	v_pk_mul_f32 v[58:59], v[58:59], v[50:51]
	v_pk_mul_f32 v[56:57], v[56:57], v[48:49]
	v_pk_mul_f32 v[46:47], v[46:47], v[38:39]
	v_pk_mul_f32 v[44:45], v[44:45], v[36:37]
	v_pk_mul_f32 v[42:43], v[42:43], v[34:35]
	v_pk_mul_f32 v[40:41], v[40:41], v[32:33]
	v_pk_mul_f32 v[30:31], v[30:31], v[22:23]
	v_pk_mul_f32 v[28:29], v[28:29], v[20:21]
	v_pk_mul_f32 v[26:27], v[26:27], v[18:19]
	v_pk_mul_f32 v[24:25], v[24:25], v[16:17]
	v_pk_mul_f32 v[14:15], v[14:15], v[6:7]
	v_pk_mul_f32 v[12:13], v[12:13], v[4:5]
	v_pk_mul_f32 v[10:11], v[10:11], v[2:3]
	v_pk_mul_f32 v[8:9], v[8:9], v[0:1]
	s_cmp_eq_u32 s45, s49
	s_waitcnt vmcnt(0)
	v_add_f32_e32 v180, v180, v181
	v_add_f32_e32 v182, v182, v183
	v_add_f32_e32 v184, v184, v185
	v_add_f32_e32 v186, v186, v187
	v_add_f32_e32 v192, v192, v193
	v_add_f32_e32 v194, v194, v195
	v_add_f32_e32 v196, v196, v197
	v_add_f32_e32 v198, v198, v199
	v_add_f32_e32 v200, v200, v201
	v_add_f32_e32 v202, v202, v203
	v_add_f32_e32 v204, v204, v205
	v_add_f32_e32 v206, v206, v207
	v_add_f32_e32 v208, v208, v209
	v_add_f32_e32 v210, v210, v211
	v_add_f32_e32 v212, v212, v213
	v_add_f32_e32 v214, v214, v215
	v_add_f32_e32 v180, v180, v182
	v_add_f32_e32 v184, v184, v186
	v_add_f32_e32 v192, v192, v194
	v_add_f32_e32 v196, v196, v198
	v_add_f32_e32 v200, v200, v202
	v_add_f32_e32 v204, v204, v206
	v_add_f32_e32 v208, v208, v210
	v_add_f32_e32 v212, v212, v214
	ds_bpermute_b32 v181, v216, v180
	ds_bpermute_b32 v185, v216, v184
	ds_bpermute_b32 v193, v216, v192
	ds_bpermute_b32 v197, v216, v196
	ds_bpermute_b32 v201, v216, v200
	ds_bpermute_b32 v205, v216, v204
	ds_bpermute_b32 v209, v216, v208
	ds_bpermute_b32 v213, v216, v212
	s_waitcnt lgkmcnt(0)
	ds_bpermute_b32 v182, v217, v180
	ds_bpermute_b32 v186, v217, v184
	ds_bpermute_b32 v194, v217, v192
	ds_bpermute_b32 v198, v217, v196
	ds_bpermute_b32 v202, v217, v200
	ds_bpermute_b32 v206, v217, v204
	ds_bpermute_b32 v210, v217, v208
	ds_bpermute_b32 v214, v217, v212
	s_waitcnt lgkmcnt(0)
	v_add_f32_e32 v181, v181, v182
	v_add_f32_e32 v185, v185, v186
	v_add_f32_e32 v193, v193, v194
	v_add_f32_e32 v197, v197, v198
	v_add_f32_e32 v201, v201, v202
	v_add_f32_e32 v205, v205, v206
	v_add_f32_e32 v209, v209, v210
	v_add_f32_e32 v213, v213, v214
	ds_bpermute_b32 v182, v218, v180
	ds_bpermute_b32 v186, v218, v184
	ds_bpermute_b32 v194, v218, v192
	ds_bpermute_b32 v198, v218, v196
	ds_bpermute_b32 v202, v218, v200
	ds_bpermute_b32 v206, v218, v204
	ds_bpermute_b32 v210, v218, v208
	ds_bpermute_b32 v214, v218, v212
	s_waitcnt lgkmcnt(0)
	v_add_f32_e32 v181, v181, v182
	v_add_f32_e32 v185, v185, v186
	v_add_f32_e32 v193, v193, v194
	v_add_f32_e32 v197, v197, v198
	v_add_f32_e32 v201, v201, v202
	v_add_f32_e32 v205, v205, v206
	v_add_f32_e32 v209, v209, v210
	v_add_f32_e32 v213, v213, v214
	ds_bpermute_b32 v182, v219, v180
	ds_bpermute_b32 v186, v219, v184
	ds_bpermute_b32 v194, v219, v192
	ds_bpermute_b32 v198, v219, v196
	ds_bpermute_b32 v202, v219, v200
	ds_bpermute_b32 v206, v219, v204
	ds_bpermute_b32 v210, v219, v208
	ds_bpermute_b32 v214, v219, v212
	s_waitcnt lgkmcnt(0)
	v_add_f32_e32 v181, v181, v182
	v_add_f32_e32 v185, v185, v186
	v_add_f32_e32 v193, v193, v194
	v_add_f32_e32 v197, v197, v198
	v_add_f32_e32 v201, v201, v202
	v_add_f32_e32 v205, v205, v206
	v_add_f32_e32 v209, v209, v210
	v_add_f32_e32 v213, v213, v214
	v_lshlrev_b64 v[150:151], 6, v[172:173]
	v_lshl_add_u64 v[150:151], s[8:9], 0, v[150:151]
	v_fmamk_f32 v139, v181, 0x3a800000, v146
	v_mul_f32_e32 v147, 0x4b800000, v139
	v_cmp_gt_f32_e32 vcc, s54, v139
	v_lshl_add_u64 v[148:149], v[170:171], 0, v[122:123]
	v_mad_i64_i32 v[154:155], s[4:5], v172, s55, v[120:121]
	v_cndmask_b32_e32 v139, v139, v147, vcc
	v_rsq_f32_e32 v139, v139
	s_nop 0
	v_mul_f32_e32 v147, 0x45800000, v139
	v_cndmask_b32_e32 v139, v139, v147, vcc
	v_mul_f32_e32 v147, 0xbfb8aa3b, v139
	v_mul_f32_e32 v139, v139, v139
	v_mul_f32_e32 v116, v116, v147
	v_mul_f32_e32 v117, v117, v147
	v_mul_f32_e32 v118, v118, v147
	v_mul_f32_e32 v119, v119, v147
	v_mul_f32_e32 v112, v112, v147
	v_mul_f32_e32 v113, v113, v147
	v_mul_f32_e32 v114, v114, v147
	v_mul_f32_e32 v115, v115, v147
	v_rcp_f32_e32 v139, v139
	v_exp_f32_e32 v116, v116
	v_exp_f32_e32 v117, v117
	v_exp_f32_e32 v118, v118
	v_exp_f32_e32 v119, v119
	v_exp_f32_e32 v112, v112
	v_exp_f32_e32 v113, v113
	v_exp_f32_e32 v114, v114
	v_exp_f32_e32 v115, v115
	v_fma_f32 v116, v116, v139, v139
	v_fma_f32 v117, v117, v139, v139
	v_fma_f32 v118, v118, v139, v139
	v_fma_f32 v119, v119, v139, v139
	v_fma_f32 v147, v112, v139, v139
	v_fma_f32 v152, v113, v139, v139
	v_fma_f32 v153, v114, v139, v139
	v_fmac_f32_e32 v139, v115, v139
	v_rcp_f32_e32 v112, v116
	v_rcp_f32_e32 v113, v117
	v_rcp_f32_e32 v114, v118
	v_rcp_f32_e32 v115, v119
	v_rcp_f32_e32 v116, v147
	v_rcp_f32_e32 v117, v152
	v_rcp_f32_e32 v118, v153
	v_rcp_f32_e32 v119, v139
	v_pk_mul_f32 v[112:113], v[124:125], v[112:113]
	v_pk_mul_f32 v[114:115], v[126:127], v[114:115]
	v_pk_mul_f32 v[116:117], v[168:169], v[116:117]
	v_pk_mul_f32 v[118:119], v[166:167], v[118:119]
	v_cvt_pk_bf16_f32 v112, v112, v113
	v_cvt_pk_bf16_f32 v113, v114, v115
	v_cvt_pk_bf16_f32 v114, v116, v117
	v_cvt_pk_bf16_f32 v115, v118, v119
	global_store_dwordx4 v[148:149], v[112:115], off
	v_or_b32_e32 v152, 32, v138
	v_ashrrev_i32_e32 v153, 31, v152
	v_fmamk_f32 v112, v185, 0x3a800000, v146
	v_mul_f32_e32 v113, 0x4b800000, v112
	v_cmp_gt_f32_e32 vcc, s54, v112
	s_nop 1
	v_cndmask_b32_e32 v112, v112, v113, vcc
	v_rsq_f32_e32 v116, v112
	v_lshl_add_u64 v[112:113], v[154:155], 0, v[122:123]
	v_mul_f32_e32 v117, 0x45800000, v116
	v_cndmask_b32_e32 v116, v116, v117, vcc
	v_mul_f32_e32 v117, 0xbfb8aa3b, v116
	v_mul_f32_e32 v116, v116, v116
	v_mul_f32_e32 v100, v100, v117
	v_mul_f32_e32 v101, v101, v117
	v_mul_f32_e32 v102, v102, v117
	v_mul_f32_e32 v103, v103, v117
	v_mul_f32_e32 v96, v96, v117
	v_mul_f32_e32 v97, v97, v117
	v_mul_f32_e32 v98, v98, v117
	v_mul_f32_e32 v99, v99, v117
	v_rcp_f32_e32 v116, v116
	v_exp_f32_e32 v100, v100
	v_exp_f32_e32 v101, v101
	v_exp_f32_e32 v102, v102
	v_exp_f32_e32 v103, v103
	v_exp_f32_e32 v96, v96
	v_exp_f32_e32 v97, v97
	v_exp_f32_e32 v98, v98
	v_exp_f32_e32 v99, v99
	v_fma_f32 v100, v100, v116, v116
	v_fma_f32 v101, v101, v116, v116
	v_fma_f32 v102, v102, v116, v116
	v_fma_f32 v103, v103, v116, v116
	v_fma_f32 v117, v96, v116, v116
	v_fma_f32 v118, v97, v116, v116
	v_fma_f32 v119, v98, v116, v116
	v_fmac_f32_e32 v116, v99, v116
	v_rcp_f32_e32 v96, v100
	v_rcp_f32_e32 v97, v101
	v_rcp_f32_e32 v98, v102
	v_rcp_f32_e32 v99, v103
	v_rcp_f32_e32 v100, v117
	v_rcp_f32_e32 v101, v118
	v_rcp_f32_e32 v102, v119
	v_rcp_f32_e32 v103, v116
	v_pk_mul_f32 v[96:97], v[108:109], v[96:97]
	v_pk_mul_f32 v[98:99], v[110:111], v[98:99]
	v_pk_mul_f32 v[100:101], v[104:105], v[100:101]
	v_pk_mul_f32 v[102:103], v[106:107], v[102:103]
	v_cvt_pk_bf16_f32 v96, v96, v97
	v_cvt_pk_bf16_f32 v97, v98, v99
	v_cvt_pk_bf16_f32 v98, v100, v101
	v_cvt_pk_bf16_f32 v99, v102, v103
	global_store_dwordx4 v[112:113], v[96:99], off
	v_or_b32_e32 v112, 48, v138
	v_mad_i64_i32 v[114:115], s[4:5], v152, s55, v[120:121]
	v_ashrrev_i32_e32 v113, 31, v112
	v_fmamk_f32 v96, v193, 0x3a800000, v146
	v_mul_f32_e32 v97, 0x4b800000, v96
	v_cmp_gt_f32_e32 vcc, s54, v96
	s_nop 1
	v_cndmask_b32_e32 v96, v96, v97, vcc
	v_rsq_f32_e32 v100, v96
	v_lshl_add_u64 v[96:97], v[114:115], 0, v[122:123]
	v_mul_f32_e32 v101, 0x45800000, v100
	v_cndmask_b32_e32 v100, v100, v101, vcc
	v_mul_f32_e32 v101, 0xbfb8aa3b, v100
	v_mul_f32_e32 v100, v100, v100
	v_mul_f32_e32 v84, v84, v101
	v_mul_f32_e32 v85, v85, v101
	v_mul_f32_e32 v86, v86, v101
	v_mul_f32_e32 v87, v87, v101
	v_mul_f32_e32 v80, v80, v101
	v_mul_f32_e32 v81, v81, v101
	v_mul_f32_e32 v82, v82, v101
	v_mul_f32_e32 v83, v83, v101
	v_rcp_f32_e32 v100, v100
	v_exp_f32_e32 v84, v84
	v_exp_f32_e32 v85, v85
	v_exp_f32_e32 v86, v86
	v_exp_f32_e32 v87, v87
	v_exp_f32_e32 v80, v80
	v_exp_f32_e32 v81, v81
	v_exp_f32_e32 v82, v82
	v_exp_f32_e32 v83, v83
	v_fma_f32 v84, v84, v100, v100
	v_fma_f32 v85, v85, v100, v100
	v_fma_f32 v86, v86, v100, v100
	v_fma_f32 v87, v87, v100, v100
	v_fma_f32 v101, v80, v100, v100
	v_fma_f32 v102, v81, v100, v100
	v_fma_f32 v103, v82, v100, v100
	v_fmac_f32_e32 v100, v83, v100
	v_rcp_f32_e32 v80, v84
	v_rcp_f32_e32 v81, v85
	v_rcp_f32_e32 v82, v86
	v_rcp_f32_e32 v83, v87
	v_rcp_f32_e32 v84, v101
	v_rcp_f32_e32 v85, v102
	v_rcp_f32_e32 v86, v103
	v_rcp_f32_e32 v87, v100
	v_pk_mul_f32 v[80:81], v[92:93], v[80:81]
	v_pk_mul_f32 v[82:83], v[94:95], v[82:83]
	v_pk_mul_f32 v[84:85], v[88:89], v[84:85]
	v_pk_mul_f32 v[86:87], v[90:91], v[86:87]
	v_cvt_pk_bf16_f32 v80, v80, v81
	v_cvt_pk_bf16_f32 v81, v82, v83
	v_cvt_pk_bf16_f32 v82, v84, v85
	v_cvt_pk_bf16_f32 v83, v86, v87
	global_store_dwordx4 v[96:97], v[80:83], off
	v_add_u32_e32 v96, 0x80, v138
	v_mad_i64_i32 v[98:99], s[4:5], v112, s55, v[120:121]
	v_ashrrev_i32_e32 v97, 31, v96
	v_fmamk_f32 v80, v197, 0x3a800000, v146
	v_mul_f32_e32 v81, 0x4b800000, v80
	v_cmp_gt_f32_e32 vcc, s54, v80
	s_nop 1
	v_cndmask_b32_e32 v80, v80, v81, vcc
	v_rsq_f32_e32 v84, v80
	v_lshl_add_u64 v[80:81], v[98:99], 0, v[122:123]
	v_mul_f32_e32 v85, 0x45800000, v84
	v_cndmask_b32_e32 v84, v84, v85, vcc
	v_mul_f32_e32 v85, 0xbfb8aa3b, v84
	v_mul_f32_e32 v84, v84, v84
	v_mul_f32_e32 v68, v68, v85
	v_mul_f32_e32 v69, v69, v85
	v_mul_f32_e32 v70, v70, v85
	v_mul_f32_e32 v71, v71, v85
	v_mul_f32_e32 v64, v64, v85
	v_mul_f32_e32 v65, v65, v85
	v_mul_f32_e32 v66, v66, v85
	v_mul_f32_e32 v67, v67, v85
	v_rcp_f32_e32 v84, v84
	v_exp_f32_e32 v68, v68
	v_exp_f32_e32 v69, v69
	v_exp_f32_e32 v70, v70
	v_exp_f32_e32 v71, v71
	v_exp_f32_e32 v64, v64
	v_exp_f32_e32 v65, v65
	v_exp_f32_e32 v66, v66
	v_exp_f32_e32 v67, v67
	v_fma_f32 v68, v68, v84, v84
	v_fma_f32 v69, v69, v84, v84
	v_fma_f32 v70, v70, v84, v84
	v_fma_f32 v71, v71, v84, v84
	v_fma_f32 v85, v64, v84, v84
	v_fma_f32 v86, v65, v84, v84
	v_fma_f32 v87, v66, v84, v84
	v_fmac_f32_e32 v84, v67, v84
	v_rcp_f32_e32 v64, v68
	v_rcp_f32_e32 v65, v69
	v_rcp_f32_e32 v66, v70
	v_rcp_f32_e32 v67, v71
	v_rcp_f32_e32 v68, v85
	v_rcp_f32_e32 v69, v86
	v_rcp_f32_e32 v70, v87
	v_rcp_f32_e32 v71, v84
	v_pk_mul_f32 v[64:65], v[76:77], v[64:65]
	v_pk_mul_f32 v[66:67], v[78:79], v[66:67]
	v_pk_mul_f32 v[68:69], v[72:73], v[68:69]
	v_pk_mul_f32 v[70:71], v[74:75], v[70:71]
	v_cvt_pk_bf16_f32 v64, v64, v65
	v_cvt_pk_bf16_f32 v65, v66, v67
	v_cvt_pk_bf16_f32 v66, v68, v69
	v_cvt_pk_bf16_f32 v67, v70, v71
	global_store_dwordx4 v[80:81], v[64:67], off
	v_add_u32_e32 v80, 0x90, v138
	v_mad_i64_i32 v[82:83], s[4:5], v96, s55, v[120:121]
	v_ashrrev_i32_e32 v81, 31, v80
	v_fmamk_f32 v64, v201, 0x3a800000, v146
	v_mul_f32_e32 v65, 0x4b800000, v64
	v_cmp_gt_f32_e32 vcc, s54, v64
	s_nop 1
	v_cndmask_b32_e32 v64, v64, v65, vcc
	v_rsq_f32_e32 v68, v64
	v_lshl_add_u64 v[64:65], v[82:83], 0, v[122:123]
	v_mul_f32_e32 v69, 0x45800000, v68
	v_cndmask_b32_e32 v68, v68, v69, vcc
	v_mul_f32_e32 v69, 0xbfb8aa3b, v68
	v_mul_f32_e32 v68, v68, v68
	v_mul_f32_e32 v52, v52, v69
	v_mul_f32_e32 v53, v53, v69
	v_mul_f32_e32 v54, v54, v69
	v_mul_f32_e32 v55, v55, v69
	v_mul_f32_e32 v48, v48, v69
	v_mul_f32_e32 v49, v49, v69
	v_mul_f32_e32 v50, v50, v69
	v_mul_f32_e32 v51, v51, v69
	v_rcp_f32_e32 v68, v68
	v_exp_f32_e32 v52, v52
	v_exp_f32_e32 v53, v53
	v_exp_f32_e32 v54, v54
	v_exp_f32_e32 v55, v55
	v_exp_f32_e32 v48, v48
	v_exp_f32_e32 v49, v49
	v_exp_f32_e32 v50, v50
	v_exp_f32_e32 v51, v51
	v_fma_f32 v52, v52, v68, v68
	v_fma_f32 v53, v53, v68, v68
	v_fma_f32 v54, v54, v68, v68
	v_fma_f32 v55, v55, v68, v68
	v_fma_f32 v69, v48, v68, v68
	v_fma_f32 v70, v49, v68, v68
	v_fma_f32 v71, v50, v68, v68
	v_fmac_f32_e32 v68, v51, v68
	v_rcp_f32_e32 v48, v52
	v_rcp_f32_e32 v49, v53
	v_rcp_f32_e32 v50, v54
	v_rcp_f32_e32 v51, v55
	v_rcp_f32_e32 v52, v69
	v_rcp_f32_e32 v53, v70
	v_rcp_f32_e32 v54, v71
	v_rcp_f32_e32 v55, v68
	v_pk_mul_f32 v[48:49], v[60:61], v[48:49]
	v_pk_mul_f32 v[50:51], v[62:63], v[50:51]
	v_pk_mul_f32 v[52:53], v[56:57], v[52:53]
	v_pk_mul_f32 v[54:55], v[58:59], v[54:55]
	v_cvt_pk_bf16_f32 v48, v48, v49
	v_cvt_pk_bf16_f32 v49, v50, v51
	v_cvt_pk_bf16_f32 v50, v52, v53
	v_cvt_pk_bf16_f32 v51, v54, v55
	global_store_dwordx4 v[64:65], v[48:51], off
	v_add_u32_e32 v64, 0xa0, v138
	v_mad_i64_i32 v[66:67], s[4:5], v80, s55, v[120:121]
	v_ashrrev_i32_e32 v65, 31, v64
	v_fmamk_f32 v48, v205, 0x3a800000, v146
	v_mul_f32_e32 v49, 0x4b800000, v48
	v_cmp_gt_f32_e32 vcc, s54, v48
	s_nop 1
	v_cndmask_b32_e32 v48, v48, v49, vcc
	v_rsq_f32_e32 v52, v48
	v_lshl_add_u64 v[48:49], v[66:67], 0, v[122:123]
	v_mul_f32_e32 v53, 0x45800000, v52
	v_cndmask_b32_e32 v52, v52, v53, vcc
	v_mul_f32_e32 v53, 0xbfb8aa3b, v52
	v_mul_f32_e32 v52, v52, v52
	v_mul_f32_e32 v36, v36, v53
	v_mul_f32_e32 v37, v37, v53
	v_mul_f32_e32 v38, v38, v53
	v_mul_f32_e32 v39, v39, v53
	v_mul_f32_e32 v32, v32, v53
	v_mul_f32_e32 v33, v33, v53
	v_mul_f32_e32 v34, v34, v53
	v_mul_f32_e32 v35, v35, v53
	v_rcp_f32_e32 v52, v52
	v_exp_f32_e32 v36, v36
	v_exp_f32_e32 v37, v37
	v_exp_f32_e32 v38, v38
	v_exp_f32_e32 v39, v39
	v_exp_f32_e32 v32, v32
	v_exp_f32_e32 v33, v33
	v_exp_f32_e32 v34, v34
	v_exp_f32_e32 v35, v35
	v_fma_f32 v36, v36, v52, v52
	v_fma_f32 v37, v37, v52, v52
	v_fma_f32 v38, v38, v52, v52
	v_fma_f32 v39, v39, v52, v52
	v_fma_f32 v53, v32, v52, v52
	v_fma_f32 v54, v33, v52, v52
	v_fma_f32 v55, v34, v52, v52
	v_fmac_f32_e32 v52, v35, v52
	v_rcp_f32_e32 v32, v36
	v_rcp_f32_e32 v33, v37
	v_rcp_f32_e32 v34, v38
	v_rcp_f32_e32 v35, v39
	v_rcp_f32_e32 v36, v53
	v_rcp_f32_e32 v37, v54
	v_rcp_f32_e32 v38, v55
	v_rcp_f32_e32 v39, v52
	v_pk_mul_f32 v[32:33], v[44:45], v[32:33]
	v_pk_mul_f32 v[34:35], v[46:47], v[34:35]
	v_pk_mul_f32 v[36:37], v[40:41], v[36:37]
	v_pk_mul_f32 v[38:39], v[42:43], v[38:39]
	v_cvt_pk_bf16_f32 v32, v32, v33
	v_cvt_pk_bf16_f32 v33, v34, v35
	v_cvt_pk_bf16_f32 v34, v36, v37
	v_cvt_pk_bf16_f32 v35, v38, v39
	global_store_dwordx4 v[48:49], v[32:35], off
	v_add_u32_e32 v48, 0xb0, v138
	v_mad_i64_i32 v[50:51], s[4:5], v64, s55, v[120:121]
	v_ashrrev_i32_e32 v49, 31, v48
	v_lshlrev_b64 v[34:35], 6, v[48:49]
	v_lshl_add_u64 v[34:35], s[8:9], 0, v[34:35]
	v_fmamk_f32 v32, v209, 0x3a800000, v146
	v_mul_f32_e32 v33, 0x4b800000, v32
	v_cmp_gt_f32_e32 vcc, s54, v32
	s_nop 1
	v_cndmask_b32_e32 v32, v32, v33, vcc
	v_rsq_f32_e32 v36, v32
	v_lshl_add_u64 v[32:33], v[50:51], 0, v[122:123]
	v_mul_f32_e32 v37, 0x45800000, v36
	v_cndmask_b32_e32 v36, v36, v37, vcc
	v_mul_f32_e32 v37, 0xbfb8aa3b, v36
	v_mul_f32_e32 v36, v36, v36
	v_mul_f32_e32 v20, v20, v37
	v_mul_f32_e32 v21, v21, v37
	v_mul_f32_e32 v22, v22, v37
	v_mul_f32_e32 v23, v23, v37
	v_mul_f32_e32 v16, v16, v37
	v_mul_f32_e32 v17, v17, v37
	v_mul_f32_e32 v18, v18, v37
	v_mul_f32_e32 v19, v19, v37
	v_rcp_f32_e32 v36, v36
	v_exp_f32_e32 v20, v20
	v_exp_f32_e32 v21, v21
	v_exp_f32_e32 v22, v22
	v_exp_f32_e32 v23, v23
	v_exp_f32_e32 v16, v16
	v_exp_f32_e32 v17, v17
	v_exp_f32_e32 v18, v18
	v_exp_f32_e32 v19, v19
	v_fma_f32 v20, v20, v36, v36
	v_fma_f32 v21, v21, v36, v36
	v_fma_f32 v22, v22, v36, v36
	v_fma_f32 v23, v23, v36, v36
	v_fma_f32 v37, v16, v36, v36
	v_fma_f32 v38, v17, v36, v36
	v_fma_f32 v39, v18, v36, v36
	v_fmac_f32_e32 v36, v19, v36
	v_rcp_f32_e32 v16, v20
	v_rcp_f32_e32 v17, v21
	v_rcp_f32_e32 v18, v22
	v_rcp_f32_e32 v19, v23
	v_rcp_f32_e32 v20, v37
	v_rcp_f32_e32 v21, v38
	v_rcp_f32_e32 v22, v39
	v_rcp_f32_e32 v23, v36
	v_pk_mul_f32 v[16:17], v[28:29], v[16:17]
	v_pk_mul_f32 v[18:19], v[30:31], v[18:19]
	v_pk_mul_f32 v[20:21], v[24:25], v[20:21]
	v_pk_mul_f32 v[22:23], v[26:27], v[22:23]
	v_cvt_pk_bf16_f32 v16, v16, v17
	v_cvt_pk_bf16_f32 v17, v18, v19
	v_cvt_pk_bf16_f32 v18, v20, v21
	v_cvt_pk_bf16_f32 v19, v22, v23
	global_store_dwordx4 v[32:33], v[16:19], off
	s_nop 1
	v_fmamk_f32 v16, v213, 0x3a800000, v146
	v_mul_f32_e32 v17, 0x4b800000, v16
	v_cmp_gt_f32_e32 vcc, s54, v16
	s_nop 1
	v_cndmask_b32_e32 v16, v16, v17, vcc
	v_rsq_f32_e32 v18, v16
	v_mad_i64_i32 v[16:17], s[4:5], v48, s55, v[120:121]
	v_lshl_add_u64 v[16:17], v[16:17], 0, v[122:123]
	v_mul_f32_e32 v19, 0x45800000, v18
	v_cndmask_b32_e32 v18, v18, v19, vcc
	v_mul_f32_e32 v19, 0xbfb8aa3b, v18
	v_mul_f32_e32 v18, v18, v18
	v_mul_f32_e32 v4, v4, v19
	v_mul_f32_e32 v5, v5, v19
	v_mul_f32_e32 v6, v6, v19
	v_mul_f32_e32 v7, v7, v19
	v_mul_f32_e32 v0, v0, v19
	v_mul_f32_e32 v1, v1, v19
	v_mul_f32_e32 v2, v2, v19
	v_mul_f32_e32 v3, v3, v19
	v_rcp_f32_e32 v18, v18
	v_exp_f32_e32 v4, v4
	v_exp_f32_e32 v5, v5
	v_exp_f32_e32 v6, v6
	v_exp_f32_e32 v7, v7
	v_exp_f32_e32 v0, v0
	v_exp_f32_e32 v1, v1
	v_exp_f32_e32 v2, v2
	v_exp_f32_e32 v3, v3
	v_fma_f32 v4, v4, v18, v18
	v_fma_f32 v5, v5, v18, v18
	v_fma_f32 v6, v6, v18, v18
	v_fma_f32 v7, v7, v18, v18
	v_fma_f32 v19, v0, v18, v18
	v_fma_f32 v20, v1, v18, v18
	v_fma_f32 v21, v2, v18, v18
	v_fmac_f32_e32 v18, v3, v18
	v_rcp_f32_e32 v0, v4
	v_rcp_f32_e32 v1, v5
	v_rcp_f32_e32 v2, v6
	v_rcp_f32_e32 v3, v7
	v_rcp_f32_e32 v4, v19
	v_rcp_f32_e32 v5, v20
	v_rcp_f32_e32 v6, v21
	v_rcp_f32_e32 v7, v18
	v_pk_mul_f32 v[0:1], v[12:13], v[0:1]
	v_pk_mul_f32 v[2:3], v[14:15], v[2:3]
	v_pk_mul_f32 v[4:5], v[8:9], v[4:5]
	v_pk_mul_f32 v[6:7], v[10:11], v[6:7]
	v_cvt_pk_bf16_f32 v0, v0, v1
	v_cvt_pk_bf16_f32 v1, v2, v3
	v_cvt_pk_bf16_f32 v2, v4, v5
	v_cvt_pk_bf16_f32 v3, v6, v7
	s_mov_b64 s[4:5], -1
	global_store_dwordx4 v[16:17], v[0:3], off
	s_cbranch_scc1 .LBB0_1457
	s_andn2_b64 vcc, exec, s[6:7]
	s_cbranch_vccnz .LBB0_1456
	s_barrier
	s_branch .LBB0_1456

.LBB0_1657:
	v_and_b32_e32 v232, 48, v146
	v_mul_u32_u24_e32 v232, 3, v232
	v_sub_u32_e32 v232, 0, v232
	v_ashrrev_i32_e32 v233, 31, v232
	v_lshl_add_u32 v140, s26, 8, v144
	v_ashrrev_i32_e32 v141, 31, v140
	v_mbcnt_lo_u32_b32 v188, -1, 0
	v_mbcnt_hi_u32_b32 v188, -1, v188
	v_lshlrev_b64 v[236:237], 6, v[140:141]
	v_lshl_add_u64 v[236:237], s[6:7], 0, v[236:237]
	v_and_b32_e32 v238, 48, v188
	v_mov_b32_e32 v239, 0
	s_mov_b64 s[98:99], 0x2000
	v_lshl_add_u64 v[236:237], v[236:237], 0, v[238:239]
	v_lshl_add_u64 v[238:239], v[236:237], 0, s[98:99]
	global_load_dwordx4 v[152:155], v[236:237], off
	global_load_dwordx4 v[156:159], v[236:237], off offset:1024
	global_load_dwordx4 v[160:163], v[236:237], off offset:2048
	global_load_dwordx4 v[164:167], v[236:237], off offset:3072
	global_load_dwordx4 v[192:195], v[238:239], off
	global_load_dwordx4 v[196:199], v[238:239], off offset:1024
	global_load_dwordx4 v[200:203], v[238:239], off offset:2048
	global_load_dwordx4 v[204:207], v[238:239], off offset:3072
	v_and_b32_e32 v189, 15, v188
	v_lshlrev_b32_e32 v189, 2, v189
	v_add_u32_e32 v190, 64, v189
	v_add_u32_e32 v191, 128, v189
	v_add_u32_e32 v188, 192, v189
	v_lshlrev_b64 v[138:139], 6, v[140:141]
	v_lshl_add_u64 v[138:139], s[6:7], 0, v[138:139]
	v_lshl_or_b32 v142, s24, 8, v146
	v_ashrrev_i32_e32 v143, 31, v142
	v_lshlrev_b64 v[168:169], 11, v[140:141]
	v_lshlrev_b64 v[138:139], 1, v[142:143]
	v_lshl_add_u64 v[170:171], s[8:9], 0, v[168:169]
	v_lshl_add_u64 v[172:173], s[0:1], 0, v[168:169]
	v_lshl_add_u64 v[176:177], v[170:171], 0, v[138:139]
	v_lshl_add_u64 v[180:181], v[172:173], 0, v[138:139]
	global_load_dwordx4 v[168:171], v[176:177], off
	global_load_dwordx4 v[172:175], v[180:181], off
	s_nop 0
	global_load_dwordx4 v[176:179], v[176:177], off offset:16
	s_nop 0
	global_load_dwordx4 v[180:183], v[180:181], off offset:16
	s_cmp_eq_u32 s25, s47
	s_mov_b64 s[24:25], -1
	s_waitcnt vmcnt(0)
	v_add_f32_e32 v152, v152, v153
	v_add_f32_e32 v154, v154, v155
	v_add_f32_e32 v156, v156, v157
	v_add_f32_e32 v158, v158, v159
	v_add_f32_e32 v160, v160, v161
	v_add_f32_e32 v162, v162, v163
	v_add_f32_e32 v164, v164, v165
	v_add_f32_e32 v166, v166, v167
	v_add_f32_e32 v192, v192, v193
	v_add_f32_e32 v194, v194, v195
	v_add_f32_e32 v196, v196, v197
	v_add_f32_e32 v198, v198, v199
	v_add_f32_e32 v200, v200, v201
	v_add_f32_e32 v202, v202, v203
	v_add_f32_e32 v204, v204, v205
	v_add_f32_e32 v206, v206, v207
	v_add_f32_e32 v152, v152, v154
	v_add_f32_e32 v156, v156, v158
	v_add_f32_e32 v160, v160, v162
	v_add_f32_e32 v164, v164, v166
	v_add_f32_e32 v192, v192, v194
	v_add_f32_e32 v196, v196, v198
	v_add_f32_e32 v200, v200, v202
	v_add_f32_e32 v204, v204, v206
	ds_bpermute_b32 v153, v189, v152
	ds_bpermute_b32 v157, v189, v156
	ds_bpermute_b32 v161, v189, v160
	ds_bpermute_b32 v165, v189, v164
	ds_bpermute_b32 v193, v189, v192
	ds_bpermute_b32 v197, v189, v196
	ds_bpermute_b32 v201, v189, v200
	ds_bpermute_b32 v205, v189, v204
	s_waitcnt lgkmcnt(0)
	ds_bpermute_b32 v154, v190, v152
	ds_bpermute_b32 v158, v190, v156
	ds_bpermute_b32 v162, v190, v160
	ds_bpermute_b32 v166, v190, v164
	ds_bpermute_b32 v194, v190, v192
	ds_bpermute_b32 v198, v190, v196
	ds_bpermute_b32 v202, v190, v200
	ds_bpermute_b32 v206, v190, v204
	s_waitcnt lgkmcnt(0)
	v_add_f32_e32 v153, v153, v154
	v_add_f32_e32 v157, v157, v158
	v_add_f32_e32 v161, v161, v162
	v_add_f32_e32 v165, v165, v166
	v_add_f32_e32 v193, v193, v194
	v_add_f32_e32 v197, v197, v198
	v_add_f32_e32 v201, v201, v202
	v_add_f32_e32 v205, v205, v206
	ds_bpermute_b32 v154, v191, v152
	ds_bpermute_b32 v158, v191, v156
	ds_bpermute_b32 v162, v191, v160
	ds_bpermute_b32 v166, v191, v164
	ds_bpermute_b32 v194, v191, v192
	ds_bpermute_b32 v198, v191, v196
	ds_bpermute_b32 v202, v191, v200
	ds_bpermute_b32 v206, v191, v204
	s_waitcnt lgkmcnt(0)
	v_add_f32_e32 v153, v153, v154
	v_add_f32_e32 v157, v157, v158
	v_add_f32_e32 v161, v161, v162
	v_add_f32_e32 v165, v165, v166
	v_add_f32_e32 v193, v193, v194
	v_add_f32_e32 v197, v197, v198
	v_add_f32_e32 v201, v201, v202
	v_add_f32_e32 v205, v205, v206
	ds_bpermute_b32 v154, v188, v152
	ds_bpermute_b32 v158, v188, v156
	ds_bpermute_b32 v162, v188, v160
	ds_bpermute_b32 v166, v188, v164
	ds_bpermute_b32 v194, v188, v192
	ds_bpermute_b32 v198, v188, v196
	ds_bpermute_b32 v202, v188, v200
	ds_bpermute_b32 v206, v188, v204
	s_waitcnt lgkmcnt(0)
	v_add_f32_e32 v208, v153, v154
	v_add_f32_e32 v209, v157, v158
	v_add_f32_e32 v210, v161, v162
	v_add_f32_e32 v211, v165, v166
	v_add_f32_e32 v212, v193, v194
	v_add_f32_e32 v213, v197, v198
	v_add_f32_e32 v214, v201, v202
	v_add_f32_e32 v215, v205, v206
	v_lshlrev_b32_e32 v158, 16, v168
	v_and_b32_e32 v159, 0xffff0000, v168
	v_fmamk_f32 v151, v208, 0x3a800000, v150
	v_mul_f32_e32 v152, 0x4b800000, v151
	v_cmp_gt_f32_e32 vcc, s51, v151
	v_and_b32_e32 v153, 0xffff0000, v176
	v_lshlrev_b32_e32 v162, 16, v172
	v_cndmask_b32_e32 v151, v151, v152, vcc
	v_rsq_f32_e32 v151, v151
	v_lshlrev_b32_e32 v152, 16, v176
	v_and_b32_e32 v163, 0xffff0000, v172
	v_lshlrev_b32_e32 v164, 16, v169
	v_mul_f32_e32 v155, 0x45800000, v151
	v_cndmask_b32_e32 v151, v151, v155, vcc
	v_mul_f32_e32 v151, 0xbfb8aa3b, v151
	v_mul_f32_e32 v127, v127, v151
	v_mul_f32_e32 v117, v117, v151
	v_mul_f32_e32 v112, v112, v151
	v_mul_f32_e32 v124, v124, v151
	v_mul_f32_e32 v121, v121, v151
	v_mul_f32_e32 v122, v122, v151
	v_exp_f32_e32 v127, v127
	v_exp_f32_e32 v117, v117
	v_exp_f32_e32 v112, v112
	v_mul_f32_e32 v113, v113, v151
	v_mul_f32_e32 v120, v120, v151
	v_mul_f32_e32 v123, v123, v151
	v_exp_f32_e32 v124, v124
	v_exp_f32_e32 v121, v121
	v_exp_f32_e32 v122, v122
	v_exp_f32_e32 v113, v113
	v_exp_f32_e32 v120, v120
	v_exp_f32_e32 v123, v123
	v_add_f32_e32 v127, 1.0, v127
	v_add_f32_e32 v176, 1.0, v117
	v_add_f32_e32 v112, 1.0, v112
	v_mul_f32_e32 v125, v125, v151
	v_mul_f32_e32 v126, v126, v151
	v_add_f32_e32 v124, 1.0, v124
	v_add_f32_e32 v156, 1.0, v121
	v_add_f32_e32 v157, 1.0, v122
	v_rcp_f32_e32 v117, v127
	v_rcp_f32_e32 v127, v176
	v_rcp_f32_e32 v176, v112
	v_add_f32_e32 v112, 1.0, v113
	v_mul_f32_e32 v116, v116, v151
	v_exp_f32_e32 v125, v125
	v_exp_f32_e32 v126, v126
	v_add_f32_e32 v155, 1.0, v120
	v_add_f32_e32 v160, 1.0, v123
	v_rcp_f32_e32 v120, v124
	v_rcp_f32_e32 v123, v156
	v_rcp_f32_e32 v124, v157
	v_lshlrev_b32_e32 v156, 16, v177
	v_and_b32_e32 v157, 0xffff0000, v177
	v_rcp_f32_e32 v177, v112
	v_mul_f32_e32 v112, v114, v151
	v_mul_f32_e32 v118, v118, v151
	v_exp_f32_e32 v116, v116
	v_mul_f32_e32 v119, v119, v151
	v_exp_f32_e32 v112, v112
	v_mul_f32_e32 v113, v115, v151
	v_exp_f32_e32 v118, v118
	v_exp_f32_e32 v119, v119
	v_exp_f32_e32 v113, v113
	v_add_f32_e32 v125, 1.0, v125
	v_add_f32_e32 v126, 1.0, v126
	v_add_f32_e32 v161, 1.0, v116
	v_rcp_f32_e32 v121, v125
	v_rcp_f32_e32 v116, v126
	v_add_f32_e32 v112, 1.0, v112
	v_rcp_f32_e32 v122, v155
	v_rcp_f32_e32 v125, v160
	v_add_f32_e32 v118, 1.0, v118
	v_add_f32_e32 v119, 1.0, v119
	v_rcp_f32_e32 v186, v112
	v_add_f32_e32 v112, 1.0, v113
	v_rcp_f32_e32 v126, v161
	v_rcp_f32_e32 v118, v118
	v_rcp_f32_e32 v119, v119
	v_rcp_f32_e32 v187, v112
	v_lshlrev_b64 v[112:113], 12, v[140:141]
	v_and_b32_e32 v165, 0xffff0000, v169
	v_lshlrev_b32_e32 v166, 16, v173
	v_and_b32_e32 v167, 0xffff0000, v173
	v_lshl_add_u64 v[114:115], s[84:85], 0, v[112:113]
	v_lshlrev_b64 v[112:113], 2, v[142:143]
	v_lshlrev_b32_e32 v168, 16, v170
	v_and_b32_e32 v169, 0xffff0000, v170
	v_lshlrev_b32_e32 v172, 16, v174
	v_and_b32_e32 v173, 0xffff0000, v174
	v_lshlrev_b32_e32 v170, 16, v171
	v_and_b32_e32 v171, 0xffff0000, v171
	v_lshlrev_b32_e32 v174, 16, v175
	v_and_b32_e32 v175, 0xffff0000, v175
	v_lshl_add_u64 v[142:143], v[114:115], 0, v[112:113]
	v_pk_fma_f32 v[218:219], v[116:117], v[164:165], v[166:167]
	v_pk_fma_f32 v[216:217], v[120:121], v[158:159], v[162:163]
	v_lshlrev_b32_e32 v154, 16, v180
	v_and_b32_e32 v155, 0xffff0000, v180
	v_lshlrev_b32_e32 v160, 16, v181
	v_and_b32_e32 v161, 0xffff0000, v181
	v_lshlrev_b32_e32 v180, 16, v178
	v_and_b32_e32 v181, 0xffff0000, v178
	v_pk_fma_f32 v[222:223], v[124:125], v[170:171], v[174:175]
	v_pk_fma_f32 v[220:221], v[122:123], v[168:169], v[172:173]
	v_lshlrev_b32_e32 v184, 16, v182
	v_and_b32_e32 v185, 0xffff0000, v182
	v_lshlrev_b32_e32 v178, 16, v179
	v_and_b32_e32 v179, 0xffff0000, v179
	v_lshlrev_b32_e32 v182, 16, v183
	v_and_b32_e32 v183, 0xffff0000, v183
	s_nop 1
	v_pk_fma_f32 v[226:227], v[118:119], v[156:157], v[160:161]
	v_pk_fma_f32 v[224:225], v[126:127], v[152:153], v[154:155]
	v_or_b32_e32 v126, 16, v140
	v_ashrrev_i32_e32 v127, 31, v126
	s_nop 0
	v_pk_fma_f32 v[230:231], v[186:187], v[178:179], v[182:183]
	v_pk_fma_f32 v[228:229], v[176:177], v[180:181], v[184:185]
	s_nop 1
	v_permlane16_swap_b32_e32 v216, v220
	v_permlane16_swap_b32_e32 v217, v221
	v_permlane16_swap_b32_e32 v218, v222
	v_permlane16_swap_b32_e32 v219, v223
	v_permlane16_swap_b32_e32 v224, v228
	v_permlane16_swap_b32_e32 v225, v229
	v_permlane16_swap_b32_e32 v226, v230
	v_permlane16_swap_b32_e32 v227, v231
	v_permlane32_swap_b32_e32 v216, v224
	v_permlane32_swap_b32_e32 v217, v225
	v_permlane32_swap_b32_e32 v218, v226
	v_permlane32_swap_b32_e32 v219, v227
	v_permlane32_swap_b32_e32 v220, v228
	v_permlane32_swap_b32_e32 v221, v229
	v_permlane32_swap_b32_e32 v222, v230
	v_permlane32_swap_b32_e32 v223, v231
	v_lshl_add_u64 v[234:235], v[142:143], 0, v[232:233]
	global_store_dwordx4 v[234:235], v[216:219], off
	global_store_dwordx4 v[234:235], v[220:223], off offset:64
	global_store_dwordx4 v[234:235], v[224:227], off offset:128
	global_store_dwordx4 v[234:235], v[228:231], off offset:192
	s_nop 1
	v_lshlrev_b64 v[114:115], 6, v[126:127]
	v_lshl_add_u64 v[142:143], s[6:7], 0, v[114:115]
	v_lshlrev_b64 v[142:143], 11, v[126:127]
	v_lshl_add_u64 v[156:157], s[8:9], 0, v[142:143]
	v_lshl_add_u64 v[142:143], s[0:1], 0, v[142:143]
	v_lshl_add_u64 v[164:165], v[156:157], 0, v[138:139]
	v_lshl_add_u64 v[142:143], v[142:143], 0, v[138:139]
	global_load_dwordx4 v[156:159], v[164:165], off
	global_load_dwordx4 v[160:163], v[142:143], off
	s_nop 0
	global_load_dwordx4 v[164:167], v[164:165], off offset:16
	s_nop 0
	global_load_dwordx4 v[168:171], v[142:143], off offset:16
	s_waitcnt vmcnt(7)
	s_waitcnt vmcnt(6)
	s_waitcnt vmcnt(5)
	s_waitcnt vmcnt(4)
	s_waitcnt vmcnt(2)
	v_lshlrev_b32_e32 v124, 16, v162
	v_and_b32_e32 v125, 0xffff0000, v162
	v_fmamk_f32 v114, v209, 0x3a800000, v150
	v_mul_f32_e32 v115, 0x4b800000, v114
	v_cmp_gt_f32_e32 vcc, s51, v114
	v_lshlrev_b32_e32 v152, 16, v163
	v_and_b32_e32 v153, 0xffff0000, v163
	v_cndmask_b32_e32 v114, v114, v115, vcc
	v_rsq_f32_e32 v116, v114
	v_lshlrev_b32_e32 v114, 16, v156
	v_and_b32_e32 v115, 0xffff0000, v156
	v_lshlrev_b32_e32 v118, 16, v157
	v_mul_f32_e32 v117, 0x45800000, v116
	v_cndmask_b32_e32 v116, v116, v117, vcc
	v_mul_f32_e32 v141, 0xbfb8aa3b, v116
	v_mul_f32_e32 v109, v109, v141
	v_mul_f32_e32 v96, v96, v141
	v_exp_f32_e32 v109, v109
	v_exp_f32_e32 v96, v96
	v_mul_f32_e32 v97, v97, v141
	v_exp_f32_e32 v97, v97
	v_add_f32_e32 v109, 1.0, v109
	v_add_f32_e32 v96, 1.0, v96
	v_mul_f32_e32 v108, v108, v141
	v_mul_f32_e32 v110, v110, v141
	v_rcp_f32_e32 v117, v109
	v_mul_f32_e32 v109, v111, v141
	v_rcp_f32_e32 v162, v96
	v_add_f32_e32 v96, 1.0, v97
	v_exp_f32_e32 v116, v108
	v_exp_f32_e32 v110, v110
	v_exp_f32_e32 v111, v109
	v_mul_f32_e32 v104, v104, v141
	v_mul_f32_e32 v105, v105, v141
	v_mul_f32_e32 v106, v106, v141
	v_mul_f32_e32 v107, v107, v141
	v_rcp_f32_e32 v163, v96
	v_mul_f32_e32 v96, v98, v141
	v_exp_f32_e32 v104, v104
	v_exp_f32_e32 v105, v105
	v_exp_f32_e32 v106, v106
	v_exp_f32_e32 v107, v107
	v_mul_f32_e32 v100, v100, v141
	v_mul_f32_e32 v101, v101, v141
	v_mul_f32_e32 v102, v102, v141
	v_mul_f32_e32 v103, v103, v141
	v_exp_f32_e32 v96, v96
	v_mul_f32_e32 v97, v99, v141
	v_exp_f32_e32 v100, v100
	v_exp_f32_e32 v101, v101
	v_exp_f32_e32 v102, v102
	v_exp_f32_e32 v103, v103
	v_exp_f32_e32 v97, v97
	v_add_f32_e32 v116, 1.0, v116
	v_add_f32_e32 v110, 1.0, v110
	v_add_f32_e32 v111, 1.0, v111
	v_rcp_f32_e32 v116, v116
	v_rcp_f32_e32 v110, v110
	v_rcp_f32_e32 v111, v111
	v_add_f32_e32 v104, 1.0, v104
	v_add_f32_e32 v105, 1.0, v105
	v_add_f32_e32 v106, 1.0, v106
	v_add_f32_e32 v107, 1.0, v107
	v_add_f32_e32 v96, 1.0, v96
	v_rcp_f32_e32 v104, v104
	v_rcp_f32_e32 v105, v105
	v_rcp_f32_e32 v106, v106
	v_rcp_f32_e32 v107, v107
	v_add_f32_e32 v100, 1.0, v100
	v_add_f32_e32 v101, 1.0, v101
	v_add_f32_e32 v102, 1.0, v102
	v_add_f32_e32 v103, 1.0, v103
	v_rcp_f32_e32 v172, v96
	v_add_f32_e32 v96, 1.0, v97
	v_rcp_f32_e32 v100, v100
	v_rcp_f32_e32 v101, v101
	v_rcp_f32_e32 v102, v102
	v_rcp_f32_e32 v103, v103
	v_rcp_f32_e32 v173, v96
	v_lshlrev_b64 v[96:97], 12, v[126:127]
	v_lshlrev_b32_e32 v108, 16, v160
	v_and_b32_e32 v109, 0xffff0000, v160
	v_and_b32_e32 v119, 0xffff0000, v157
	v_lshlrev_b32_e32 v120, 16, v161
	v_and_b32_e32 v121, 0xffff0000, v161
	v_lshl_add_u64 v[96:97], s[84:85], 0, v[96:97]
	v_lshlrev_b32_e32 v122, 16, v158
	v_and_b32_e32 v123, 0xffff0000, v158
	v_lshlrev_b32_e32 v142, 16, v159
	v_and_b32_e32 v143, 0xffff0000, v159
	v_lshl_add_u64 v[126:127], v[96:97], 0, v[112:113]
	v_pk_fma_f32 v[218:219], v[110:111], v[118:119], v[120:121]
	v_pk_fma_f32 v[216:217], v[116:117], v[114:115], v[108:109]
	s_waitcnt vmcnt(1)
	v_lshlrev_b32_e32 v154, 16, v164
	v_and_b32_e32 v155, 0xffff0000, v164
	s_waitcnt vmcnt(0)
	v_lshlrev_b32_e32 v156, 16, v168
	v_and_b32_e32 v157, 0xffff0000, v168
	v_lshlrev_b32_e32 v158, 16, v165
	v_and_b32_e32 v159, 0xffff0000, v165
	v_lshlrev_b32_e32 v160, 16, v169
	v_and_b32_e32 v161, 0xffff0000, v169
	v_lshlrev_b32_e32 v164, 16, v166
	v_and_b32_e32 v165, 0xffff0000, v166
	v_pk_fma_f32 v[222:223], v[106:107], v[142:143], v[152:153]
	v_pk_fma_f32 v[220:221], v[104:105], v[122:123], v[124:125]
	v_lshlrev_b32_e32 v168, 16, v170
	v_and_b32_e32 v169, 0xffff0000, v170
	v_lshlrev_b32_e32 v166, 16, v167
	v_and_b32_e32 v167, 0xffff0000, v167
	v_lshlrev_b32_e32 v170, 16, v171
	v_and_b32_e32 v171, 0xffff0000, v171
	s_nop 1
	v_pk_fma_f32 v[226:227], v[102:103], v[158:159], v[160:161]
	v_pk_fma_f32 v[224:225], v[100:101], v[154:155], v[156:157]
	s_nop 1
	v_pk_fma_f32 v[230:231], v[172:173], v[166:167], v[170:171]
	v_pk_fma_f32 v[228:229], v[162:163], v[164:165], v[168:169]
	s_nop 1
	v_permlane16_swap_b32_e32 v216, v220
	v_permlane16_swap_b32_e32 v217, v221
	v_permlane16_swap_b32_e32 v218, v222
	v_permlane16_swap_b32_e32 v219, v223
	v_permlane16_swap_b32_e32 v224, v228
	v_permlane16_swap_b32_e32 v225, v229
	v_permlane16_swap_b32_e32 v226, v230
	v_permlane16_swap_b32_e32 v227, v231
	v_permlane32_swap_b32_e32 v216, v224
	v_permlane32_swap_b32_e32 v217, v225
	v_permlane32_swap_b32_e32 v218, v226
	v_permlane32_swap_b32_e32 v219, v227
	v_permlane32_swap_b32_e32 v220, v228
	v_permlane32_swap_b32_e32 v221, v229
	v_permlane32_swap_b32_e32 v222, v230
	v_permlane32_swap_b32_e32 v223, v231
	v_lshl_add_u64 v[234:235], v[126:127], 0, v[232:233]
	global_store_dwordx4 v[234:235], v[216:219], off
	global_store_dwordx4 v[234:235], v[220:223], off offset:64
	global_store_dwordx4 v[234:235], v[224:227], off offset:128
	global_store_dwordx4 v[234:235], v[228:231], off offset:192
	v_or_b32_e32 v126, 32, v140
	v_ashrrev_i32_e32 v127, 31, v126
	v_lshlrev_b64 v[96:97], 6, v[126:127]
	v_lshl_add_u64 v[108:109], s[6:7], 0, v[96:97]
	s_nop 0
	v_lshlrev_b64 v[114:115], 11, v[126:127]
	v_lshl_add_u64 v[116:117], s[8:9], 0, v[114:115]
	v_lshl_add_u64 v[122:123], v[116:117], 0, v[138:139]
	v_lshl_add_u64 v[118:119], s[0:1], 0, v[114:115]
	global_load_dwordx4 v[114:117], v[122:123], off
	v_lshl_add_u64 v[142:143], v[118:119], 0, v[138:139]
	global_load_dwordx4 v[118:121], v[142:143], off
	s_nop 0
	global_load_dwordx4 v[122:125], v[122:123], off offset:16
	s_nop 0
	global_load_dwordx4 v[152:155], v[142:143], off offset:16
	s_waitcnt vmcnt(7)
	s_waitcnt vmcnt(6)
	s_waitcnt vmcnt(5)
	s_waitcnt vmcnt(4)
	s_waitcnt vmcnt(3)
	v_lshlrev_b32_e32 v100, 16, v115
	v_and_b32_e32 v101, 0xffff0000, v115
	v_fmamk_f32 v96, v210, 0x3a800000, v150
	v_mul_f32_e32 v97, 0x4b800000, v96
	v_cmp_gt_f32_e32 vcc, s51, v96
	s_waitcnt vmcnt(1)
	v_and_b32_e32 v115, 0xffff0000, v122
	v_lshlrev_b32_e32 v98, 16, v118
	v_cndmask_b32_e32 v96, v96, v97, vcc
	v_rsq_f32_e32 v96, v96
	v_and_b32_e32 v99, 0xffff0000, v118
	v_lshlrev_b32_e32 v102, 16, v119
	v_and_b32_e32 v103, 0xffff0000, v119
	v_mul_f32_e32 v97, 0x45800000, v96
	v_cndmask_b32_e32 v96, v96, v97, vcc
	v_mul_f32_e32 v141, 0xbfb8aa3b, v96
	v_mul_f32_e32 v80, v80, v141
	v_exp_f32_e32 v80, v80
	v_mul_f32_e32 v81, v81, v141
	v_exp_f32_e32 v81, v81
	v_mul_f32_e32 v92, v92, v141
	v_add_f32_e32 v80, 1.0, v80
	v_mul_f32_e32 v93, v93, v141
	v_lshlrev_b32_e32 v96, 16, v114
	v_and_b32_e32 v97, 0xffff0000, v114
	v_mul_f32_e32 v94, v94, v141
	v_mul_f32_e32 v95, v95, v141
	v_lshlrev_b32_e32 v114, 16, v122
	v_rcp_f32_e32 v122, v80
	v_add_f32_e32 v80, 1.0, v81
	v_exp_f32_e32 v92, v92
	v_exp_f32_e32 v93, v93
	v_exp_f32_e32 v94, v94
	v_exp_f32_e32 v95, v95
	v_mul_f32_e32 v88, v88, v141
	v_mul_f32_e32 v89, v89, v141
	v_mul_f32_e32 v90, v90, v141
	v_mul_f32_e32 v91, v91, v141
	v_lshlrev_b32_e32 v118, 16, v123
	v_and_b32_e32 v119, 0xffff0000, v123
	v_rcp_f32_e32 v123, v80
	v_mul_f32_e32 v80, v82, v141
	v_exp_f32_e32 v88, v88
	v_exp_f32_e32 v89, v89
	v_exp_f32_e32 v90, v90
	v_exp_f32_e32 v91, v91
	v_mul_f32_e32 v84, v84, v141
	v_mul_f32_e32 v85, v85, v141
	v_mul_f32_e32 v86, v86, v141
	v_mul_f32_e32 v87, v87, v141
	v_exp_f32_e32 v80, v80
	v_mul_f32_e32 v81, v83, v141
	v_exp_f32_e32 v84, v84
	v_exp_f32_e32 v85, v85
	v_exp_f32_e32 v86, v86
	v_exp_f32_e32 v87, v87
	v_exp_f32_e32 v81, v81
	v_add_f32_e32 v92, 1.0, v92
	v_add_f32_e32 v93, 1.0, v93
	v_add_f32_e32 v94, 1.0, v94
	v_add_f32_e32 v95, 1.0, v95
	v_rcp_f32_e32 v92, v92
	v_rcp_f32_e32 v93, v93
	v_rcp_f32_e32 v94, v94
	v_rcp_f32_e32 v95, v95
	v_add_f32_e32 v88, 1.0, v88
	v_add_f32_e32 v89, 1.0, v89
	v_add_f32_e32 v90, 1.0, v90
	v_add_f32_e32 v91, 1.0, v91
	v_add_f32_e32 v80, 1.0, v80
	v_rcp_f32_e32 v88, v88
	v_rcp_f32_e32 v89, v89
	v_rcp_f32_e32 v90, v90
	v_rcp_f32_e32 v91, v91
	v_add_f32_e32 v84, 1.0, v84
	v_add_f32_e32 v85, 1.0, v85
	v_add_f32_e32 v86, 1.0, v86
	v_add_f32_e32 v87, 1.0, v87
	v_rcp_f32_e32 v156, v80
	v_add_f32_e32 v80, 1.0, v81
	v_rcp_f32_e32 v84, v84
	v_rcp_f32_e32 v85, v85
	v_rcp_f32_e32 v86, v86
	v_rcp_f32_e32 v87, v87
	v_rcp_f32_e32 v157, v80
	v_lshlrev_b64 v[80:81], 12, v[126:127]
	v_lshl_add_u64 v[80:81], s[84:85], 0, v[80:81]
	v_lshlrev_b32_e32 v104, 16, v116
	v_and_b32_e32 v105, 0xffff0000, v116
	v_lshlrev_b32_e32 v106, 16, v120
	v_and_b32_e32 v107, 0xffff0000, v120
	v_lshlrev_b32_e32 v108, 16, v117
	v_and_b32_e32 v109, 0xffff0000, v117
	v_lshlrev_b32_e32 v110, 16, v121
	v_and_b32_e32 v111, 0xffff0000, v121
	v_lshl_add_u64 v[126:127], v[80:81], 0, v[112:113]
	v_pk_fma_f32 v[218:219], v[94:95], v[100:101], v[102:103]
	v_pk_fma_f32 v[216:217], v[92:93], v[96:97], v[98:99]
	s_waitcnt vmcnt(0)
	v_lshlrev_b32_e32 v116, 16, v152
	v_and_b32_e32 v117, 0xffff0000, v152
	v_lshlrev_b32_e32 v120, 16, v153
	v_and_b32_e32 v121, 0xffff0000, v153
	v_lshlrev_b32_e32 v142, 16, v124
	v_and_b32_e32 v143, 0xffff0000, v124
	v_pk_fma_f32 v[222:223], v[90:91], v[108:109], v[110:111]
	v_pk_fma_f32 v[220:221], v[88:89], v[104:105], v[106:107]
	v_lshlrev_b32_e32 v152, 16, v154
	v_and_b32_e32 v153, 0xffff0000, v154
	v_lshlrev_b32_e32 v124, 16, v125
	v_and_b32_e32 v125, 0xffff0000, v125
	v_lshlrev_b32_e32 v154, 16, v155
	v_and_b32_e32 v155, 0xffff0000, v155
	s_nop 1
	v_pk_fma_f32 v[226:227], v[86:87], v[118:119], v[120:121]
	v_pk_fma_f32 v[224:225], v[84:85], v[114:115], v[116:117]
	v_or_b32_e32 v114, 48, v140
	v_ashrrev_i32_e32 v115, 31, v114
	s_nop 0
	v_pk_fma_f32 v[230:231], v[156:157], v[124:125], v[154:155]
	v_pk_fma_f32 v[228:229], v[122:123], v[142:143], v[152:153]
	s_nop 1
	v_permlane16_swap_b32_e32 v216, v220
	v_permlane16_swap_b32_e32 v217, v221
	v_permlane16_swap_b32_e32 v218, v222
	v_permlane16_swap_b32_e32 v219, v223
	v_permlane16_swap_b32_e32 v224, v228
	v_permlane16_swap_b32_e32 v225, v229
	v_permlane16_swap_b32_e32 v226, v230
	v_permlane16_swap_b32_e32 v227, v231
	v_permlane32_swap_b32_e32 v216, v224
	v_permlane32_swap_b32_e32 v217, v225
	v_permlane32_swap_b32_e32 v218, v226
	v_permlane32_swap_b32_e32 v219, v227
	v_permlane32_swap_b32_e32 v220, v228
	v_permlane32_swap_b32_e32 v221, v229
	v_permlane32_swap_b32_e32 v222, v230
	v_permlane32_swap_b32_e32 v223, v231
	v_lshl_add_u64 v[234:235], v[126:127], 0, v[232:233]
	global_store_dwordx4 v[234:235], v[216:219], off
	global_store_dwordx4 v[234:235], v[220:223], off offset:64
	global_store_dwordx4 v[234:235], v[224:227], off offset:128
	global_store_dwordx4 v[234:235], v[228:231], off offset:192
	s_nop 1
	v_lshlrev_b64 v[80:81], 6, v[114:115]
	v_lshl_add_u64 v[96:97], s[6:7], 0, v[80:81]
	v_lshlrev_b64 v[96:97], 11, v[114:115]
	v_lshl_add_u64 v[98:99], s[8:9], 0, v[96:97]
	v_lshl_add_u64 v[104:105], v[98:99], 0, v[138:139]
	v_lshl_add_u64 v[100:101], s[0:1], 0, v[96:97]
	global_load_dwordx4 v[96:99], v[104:105], off
	v_lshl_add_u64 v[108:109], v[100:101], 0, v[138:139]
	global_load_dwordx4 v[100:103], v[108:109], off
	s_nop 0
	global_load_dwordx4 v[104:107], v[104:105], off offset:16
	s_nop 0
	global_load_dwordx4 v[108:111], v[108:109], off offset:16
	s_waitcnt vmcnt(7)
	s_waitcnt vmcnt(6)
	s_waitcnt vmcnt(5)
	s_waitcnt vmcnt(4)
	s_waitcnt vmcnt(3)
	v_lshlrev_b32_e32 v84, 16, v97
	v_and_b32_e32 v85, 0xffff0000, v97
	v_fmamk_f32 v80, v211, 0x3a800000, v150
	v_mul_f32_e32 v81, 0x4b800000, v80
	v_cmp_gt_f32_e32 vcc, s51, v80
	s_waitcnt vmcnt(1)
	v_and_b32_e32 v97, 0xffff0000, v104
	v_lshlrev_b32_e32 v82, 16, v100
	v_cndmask_b32_e32 v80, v80, v81, vcc
	v_rsq_f32_e32 v80, v80
	v_and_b32_e32 v83, 0xffff0000, v100
	v_lshlrev_b32_e32 v86, 16, v101
	v_and_b32_e32 v87, 0xffff0000, v101
	v_mul_f32_e32 v81, 0x45800000, v80
	v_cndmask_b32_e32 v80, v80, v81, vcc
	v_mul_f32_e32 v117, 0xbfb8aa3b, v80
	v_mul_f32_e32 v64, v64, v117
	v_exp_f32_e32 v64, v64
	v_mul_f32_e32 v65, v65, v117
	v_exp_f32_e32 v65, v65
	v_mul_f32_e32 v76, v76, v117
	v_add_f32_e32 v64, 1.0, v64
	v_mul_f32_e32 v77, v77, v117
	v_lshlrev_b32_e32 v80, 16, v96
	v_and_b32_e32 v81, 0xffff0000, v96
	v_mul_f32_e32 v78, v78, v117
	v_mul_f32_e32 v79, v79, v117
	v_lshlrev_b32_e32 v96, 16, v104
	v_rcp_f32_e32 v104, v64
	v_add_f32_e32 v64, 1.0, v65
	v_exp_f32_e32 v76, v76
	v_exp_f32_e32 v77, v77
	v_exp_f32_e32 v78, v78
	v_exp_f32_e32 v79, v79
	v_mul_f32_e32 v72, v72, v117
	v_mul_f32_e32 v73, v73, v117
	v_mul_f32_e32 v74, v74, v117
	v_mul_f32_e32 v75, v75, v117
	v_lshlrev_b32_e32 v100, 16, v105
	v_and_b32_e32 v101, 0xffff0000, v105
	v_rcp_f32_e32 v105, v64
	v_mul_f32_e32 v64, v66, v117
	v_exp_f32_e32 v72, v72
	v_exp_f32_e32 v73, v73
	v_exp_f32_e32 v74, v74
	v_exp_f32_e32 v75, v75
	v_mul_f32_e32 v68, v68, v117
	v_mul_f32_e32 v69, v69, v117
	v_mul_f32_e32 v70, v70, v117
	v_mul_f32_e32 v71, v71, v117
	v_exp_f32_e32 v64, v64
	v_mul_f32_e32 v65, v67, v117
	v_exp_f32_e32 v68, v68
	v_exp_f32_e32 v69, v69
	v_exp_f32_e32 v70, v70
	v_exp_f32_e32 v71, v71
	v_exp_f32_e32 v65, v65
	v_add_f32_e32 v76, 1.0, v76
	v_add_f32_e32 v77, 1.0, v77
	v_add_f32_e32 v78, 1.0, v78
	v_add_f32_e32 v79, 1.0, v79
	v_rcp_f32_e32 v76, v76
	v_rcp_f32_e32 v77, v77
	v_rcp_f32_e32 v78, v78
	v_rcp_f32_e32 v79, v79
	v_add_f32_e32 v72, 1.0, v72
	v_add_f32_e32 v73, 1.0, v73
	v_add_f32_e32 v74, 1.0, v74
	v_add_f32_e32 v75, 1.0, v75
	v_add_f32_e32 v64, 1.0, v64
	v_rcp_f32_e32 v72, v72
	v_rcp_f32_e32 v73, v73
	v_rcp_f32_e32 v74, v74
	v_rcp_f32_e32 v75, v75
	v_add_f32_e32 v68, 1.0, v68
	v_add_f32_e32 v69, 1.0, v69
	v_add_f32_e32 v70, 1.0, v70
	v_add_f32_e32 v71, 1.0, v71
	v_rcp_f32_e32 v118, v64
	v_add_f32_e32 v64, 1.0, v65
	v_rcp_f32_e32 v68, v68
	v_rcp_f32_e32 v69, v69
	v_rcp_f32_e32 v70, v70
	v_rcp_f32_e32 v71, v71
	v_rcp_f32_e32 v119, v64
	v_lshlrev_b64 v[64:65], 12, v[114:115]
	v_lshl_add_u64 v[64:65], s[84:85], 0, v[64:65]
	v_lshlrev_b32_e32 v88, 16, v98
	v_and_b32_e32 v89, 0xffff0000, v98
	v_lshlrev_b32_e32 v90, 16, v102
	v_and_b32_e32 v91, 0xffff0000, v102
	v_lshlrev_b32_e32 v92, 16, v99
	v_and_b32_e32 v93, 0xffff0000, v99
	v_lshlrev_b32_e32 v94, 16, v103
	v_and_b32_e32 v95, 0xffff0000, v103
	v_lshl_add_u64 v[114:115], v[64:65], 0, v[112:113]
	v_pk_fma_f32 v[218:219], v[78:79], v[84:85], v[86:87]
	v_pk_fma_f32 v[216:217], v[76:77], v[80:81], v[82:83]
	s_waitcnt vmcnt(0)
	v_lshlrev_b32_e32 v98, 16, v108
	v_and_b32_e32 v99, 0xffff0000, v108
	v_lshlrev_b32_e32 v102, 16, v109
	v_and_b32_e32 v103, 0xffff0000, v109
	v_lshlrev_b32_e32 v108, 16, v106
	v_and_b32_e32 v109, 0xffff0000, v106
	v_pk_fma_f32 v[222:223], v[74:75], v[92:93], v[94:95]
	v_pk_fma_f32 v[220:221], v[72:73], v[88:89], v[90:91]
	v_lshlrev_b32_e32 v116, 16, v110
	v_and_b32_e32 v117, 0xffff0000, v110
	v_lshlrev_b32_e32 v106, 16, v107
	v_and_b32_e32 v107, 0xffff0000, v107
	v_lshlrev_b32_e32 v110, 16, v111
	v_and_b32_e32 v111, 0xffff0000, v111
	s_nop 1
	v_pk_fma_f32 v[226:227], v[70:71], v[100:101], v[102:103]
	v_pk_fma_f32 v[224:225], v[68:69], v[96:97], v[98:99]
	v_add_u32_e32 v96, 0x80, v140
	v_ashrrev_i32_e32 v97, 31, v96
	s_nop 0
	v_pk_fma_f32 v[230:231], v[118:119], v[106:107], v[110:111]
	v_pk_fma_f32 v[228:229], v[104:105], v[108:109], v[116:117]
	s_nop 1
	v_permlane16_swap_b32_e32 v216, v220
	v_permlane16_swap_b32_e32 v217, v221
	v_permlane16_swap_b32_e32 v218, v222
	v_permlane16_swap_b32_e32 v219, v223
	v_permlane16_swap_b32_e32 v224, v228
	v_permlane16_swap_b32_e32 v225, v229
	v_permlane16_swap_b32_e32 v226, v230
	v_permlane16_swap_b32_e32 v227, v231
	v_permlane32_swap_b32_e32 v216, v224
	v_permlane32_swap_b32_e32 v217, v225
	v_permlane32_swap_b32_e32 v218, v226
	v_permlane32_swap_b32_e32 v219, v227
	v_permlane32_swap_b32_e32 v220, v228
	v_permlane32_swap_b32_e32 v221, v229
	v_permlane32_swap_b32_e32 v222, v230
	v_permlane32_swap_b32_e32 v223, v231
	v_lshl_add_u64 v[234:235], v[114:115], 0, v[232:233]
	global_store_dwordx4 v[234:235], v[216:219], off
	global_store_dwordx4 v[234:235], v[220:223], off offset:64
	global_store_dwordx4 v[234:235], v[224:227], off offset:128
	global_store_dwordx4 v[234:235], v[228:231], off offset:192
	s_nop 1
	v_lshlrev_b64 v[64:65], 6, v[96:97]
	v_lshl_add_u64 v[80:81], s[6:7], 0, v[64:65]
	v_lshlrev_b64 v[80:81], 11, v[96:97]
	v_lshl_add_u64 v[82:83], s[8:9], 0, v[80:81]
	v_lshl_add_u64 v[98:99], v[82:83], 0, v[138:139]
	v_lshl_add_u64 v[84:85], s[0:1], 0, v[80:81]
	global_load_dwordx4 v[80:83], v[98:99], off
	v_lshl_add_u64 v[100:101], v[84:85], 0, v[138:139]
	global_load_dwordx4 v[84:87], v[100:101], off
	global_load_dwordx4 v[88:91], v[98:99], off offset:16
	global_load_dwordx4 v[92:95], v[100:101], off offset:16
	s_waitcnt vmcnt(7)
	s_waitcnt vmcnt(6)
	s_waitcnt vmcnt(5)
	s_waitcnt vmcnt(4)
	s_waitcnt vmcnt(3)
	v_lshlrev_b32_e32 v68, 16, v81
	v_and_b32_e32 v69, 0xffff0000, v81
	v_fmamk_f32 v64, v212, 0x3a800000, v150
	v_mul_f32_e32 v65, 0x4b800000, v64
	v_cmp_gt_f32_e32 vcc, s51, v64
	s_waitcnt vmcnt(1)
	v_and_b32_e32 v81, 0xffff0000, v88
	v_lshlrev_b32_e32 v66, 16, v84
	v_cndmask_b32_e32 v64, v64, v65, vcc
	v_rsq_f32_e32 v64, v64
	v_and_b32_e32 v67, 0xffff0000, v84
	v_lshlrev_b32_e32 v70, 16, v85
	v_and_b32_e32 v71, 0xffff0000, v85
	v_mul_f32_e32 v65, 0x45800000, v64
	v_cndmask_b32_e32 v64, v64, v65, vcc
	v_mul_f32_e32 v99, 0xbfb8aa3b, v64
	v_mul_f32_e32 v48, v48, v99
	v_exp_f32_e32 v48, v48
	v_mul_f32_e32 v49, v49, v99
	v_exp_f32_e32 v49, v49
	v_mul_f32_e32 v60, v60, v99
	v_add_f32_e32 v48, 1.0, v48
	v_mul_f32_e32 v61, v61, v99
	v_lshlrev_b32_e32 v64, 16, v80
	v_and_b32_e32 v65, 0xffff0000, v80
	v_mul_f32_e32 v62, v62, v99
	v_mul_f32_e32 v63, v63, v99
	v_lshlrev_b32_e32 v80, 16, v88
	v_rcp_f32_e32 v88, v48
	v_add_f32_e32 v48, 1.0, v49
	v_exp_f32_e32 v60, v60
	v_exp_f32_e32 v61, v61
	v_exp_f32_e32 v62, v62
	v_exp_f32_e32 v63, v63
	v_mul_f32_e32 v56, v56, v99
	v_mul_f32_e32 v57, v57, v99
	v_mul_f32_e32 v58, v58, v99
	v_mul_f32_e32 v59, v59, v99
	v_lshlrev_b32_e32 v84, 16, v89
	v_and_b32_e32 v85, 0xffff0000, v89
	v_rcp_f32_e32 v89, v48
	v_mul_f32_e32 v48, v50, v99
	v_exp_f32_e32 v56, v56
	v_exp_f32_e32 v57, v57
	v_exp_f32_e32 v58, v58
	v_exp_f32_e32 v59, v59
	v_mul_f32_e32 v52, v52, v99
	v_mul_f32_e32 v53, v53, v99
	v_mul_f32_e32 v54, v54, v99
	v_mul_f32_e32 v55, v55, v99
	v_exp_f32_e32 v48, v48
	v_mul_f32_e32 v49, v51, v99
	v_exp_f32_e32 v52, v52
	v_exp_f32_e32 v53, v53
	v_exp_f32_e32 v54, v54
	v_exp_f32_e32 v55, v55
	v_exp_f32_e32 v49, v49
	v_add_f32_e32 v60, 1.0, v60
	v_add_f32_e32 v61, 1.0, v61
	v_add_f32_e32 v62, 1.0, v62
	v_add_f32_e32 v63, 1.0, v63
	v_rcp_f32_e32 v60, v60
	v_rcp_f32_e32 v61, v61
	v_rcp_f32_e32 v62, v62
	v_rcp_f32_e32 v63, v63
	v_add_f32_e32 v56, 1.0, v56
	v_add_f32_e32 v57, 1.0, v57
	v_add_f32_e32 v58, 1.0, v58
	v_add_f32_e32 v59, 1.0, v59
	v_add_f32_e32 v48, 1.0, v48
	v_rcp_f32_e32 v56, v56
	v_rcp_f32_e32 v57, v57
	v_rcp_f32_e32 v58, v58
	v_rcp_f32_e32 v59, v59
	v_add_f32_e32 v52, 1.0, v52
	v_add_f32_e32 v53, 1.0, v53
	v_add_f32_e32 v54, 1.0, v54
	v_add_f32_e32 v55, 1.0, v55
	v_rcp_f32_e32 v100, v48
	v_add_f32_e32 v48, 1.0, v49
	v_rcp_f32_e32 v52, v52
	v_rcp_f32_e32 v53, v53
	v_rcp_f32_e32 v54, v54
	v_rcp_f32_e32 v55, v55
	v_rcp_f32_e32 v101, v48
	v_lshlrev_b64 v[48:49], 12, v[96:97]
	v_lshl_add_u64 v[48:49], s[84:85], 0, v[48:49]
	v_lshlrev_b32_e32 v72, 16, v82
	v_and_b32_e32 v73, 0xffff0000, v82
	v_lshlrev_b32_e32 v74, 16, v86
	v_and_b32_e32 v75, 0xffff0000, v86
	v_lshlrev_b32_e32 v76, 16, v83
	v_and_b32_e32 v77, 0xffff0000, v83
	v_lshlrev_b32_e32 v78, 16, v87
	v_and_b32_e32 v79, 0xffff0000, v87
	v_lshl_add_u64 v[96:97], v[48:49], 0, v[112:113]
	v_pk_fma_f32 v[218:219], v[62:63], v[68:69], v[70:71]
	v_pk_fma_f32 v[216:217], v[60:61], v[64:65], v[66:67]
	s_waitcnt vmcnt(0)
	v_lshlrev_b32_e32 v82, 16, v92
	v_and_b32_e32 v83, 0xffff0000, v92
	v_lshlrev_b32_e32 v86, 16, v93
	v_and_b32_e32 v87, 0xffff0000, v93
	v_lshlrev_b32_e32 v92, 16, v90
	v_and_b32_e32 v93, 0xffff0000, v90
	v_pk_fma_f32 v[222:223], v[58:59], v[76:77], v[78:79]
	v_pk_fma_f32 v[220:221], v[56:57], v[72:73], v[74:75]
	v_lshlrev_b32_e32 v98, 16, v94
	v_and_b32_e32 v99, 0xffff0000, v94
	v_lshlrev_b32_e32 v90, 16, v91
	v_and_b32_e32 v91, 0xffff0000, v91
	v_lshlrev_b32_e32 v94, 16, v95
	v_and_b32_e32 v95, 0xffff0000, v95
	s_nop 1
	v_pk_fma_f32 v[226:227], v[54:55], v[84:85], v[86:87]
	v_pk_fma_f32 v[224:225], v[52:53], v[80:81], v[82:83]
	v_add_u32_e32 v80, 0x90, v140
	v_ashrrev_i32_e32 v81, 31, v80
	s_nop 0
	v_pk_fma_f32 v[230:231], v[100:101], v[90:91], v[94:95]
	v_pk_fma_f32 v[228:229], v[88:89], v[92:93], v[98:99]
	s_nop 1
	v_permlane16_swap_b32_e32 v216, v220
	v_permlane16_swap_b32_e32 v217, v221
	v_permlane16_swap_b32_e32 v218, v222
	v_permlane16_swap_b32_e32 v219, v223
	v_permlane16_swap_b32_e32 v224, v228
	v_permlane16_swap_b32_e32 v225, v229
	v_permlane16_swap_b32_e32 v226, v230
	v_permlane16_swap_b32_e32 v227, v231
	v_permlane32_swap_b32_e32 v216, v224
	v_permlane32_swap_b32_e32 v217, v225
	v_permlane32_swap_b32_e32 v218, v226
	v_permlane32_swap_b32_e32 v219, v227
	v_permlane32_swap_b32_e32 v220, v228
	v_permlane32_swap_b32_e32 v221, v229
	v_permlane32_swap_b32_e32 v222, v230
	v_permlane32_swap_b32_e32 v223, v231
	v_lshl_add_u64 v[234:235], v[96:97], 0, v[232:233]
	global_store_dwordx4 v[234:235], v[216:219], off
	global_store_dwordx4 v[234:235], v[220:223], off offset:64
	global_store_dwordx4 v[234:235], v[224:227], off offset:128
	global_store_dwordx4 v[234:235], v[228:231], off offset:192
	s_nop 1
	v_lshlrev_b64 v[48:49], 6, v[80:81]
	v_lshl_add_u64 v[64:65], s[6:7], 0, v[48:49]
	v_lshlrev_b64 v[64:65], 11, v[80:81]
	v_lshl_add_u64 v[66:67], s[8:9], 0, v[64:65]
	v_lshl_add_u64 v[82:83], v[66:67], 0, v[138:139]
	v_lshl_add_u64 v[68:69], s[0:1], 0, v[64:65]
	global_load_dwordx4 v[64:67], v[82:83], off
	v_lshl_add_u64 v[84:85], v[68:69], 0, v[138:139]
	global_load_dwordx4 v[68:71], v[84:85], off
	global_load_dwordx4 v[72:75], v[82:83], off offset:16
	global_load_dwordx4 v[76:79], v[84:85], off offset:16
	s_waitcnt vmcnt(7)
	s_waitcnt vmcnt(6)
	s_waitcnt vmcnt(5)
	s_waitcnt vmcnt(4)
	s_waitcnt vmcnt(3)
	v_lshlrev_b32_e32 v52, 16, v65
	v_and_b32_e32 v53, 0xffff0000, v65
	v_fmamk_f32 v48, v213, 0x3a800000, v150
	v_mul_f32_e32 v49, 0x4b800000, v48
	v_cmp_gt_f32_e32 vcc, s51, v48
	s_waitcnt vmcnt(1)
	v_and_b32_e32 v65, 0xffff0000, v72
	v_lshlrev_b32_e32 v50, 16, v68
	v_cndmask_b32_e32 v48, v48, v49, vcc
	v_rsq_f32_e32 v48, v48
	v_and_b32_e32 v51, 0xffff0000, v68
	v_lshlrev_b32_e32 v54, 16, v69
	v_and_b32_e32 v55, 0xffff0000, v69
	v_mul_f32_e32 v49, 0x45800000, v48
	v_cndmask_b32_e32 v48, v48, v49, vcc
	v_mul_f32_e32 v83, 0xbfb8aa3b, v48
	v_mul_f32_e32 v32, v32, v83
	v_exp_f32_e32 v32, v32
	v_mul_f32_e32 v33, v33, v83
	v_exp_f32_e32 v33, v33
	v_mul_f32_e32 v44, v44, v83
	v_add_f32_e32 v32, 1.0, v32
	v_mul_f32_e32 v45, v45, v83
	v_lshlrev_b32_e32 v48, 16, v64
	v_and_b32_e32 v49, 0xffff0000, v64
	v_mul_f32_e32 v46, v46, v83
	v_mul_f32_e32 v47, v47, v83
	v_lshlrev_b32_e32 v64, 16, v72
	v_rcp_f32_e32 v72, v32
	v_add_f32_e32 v32, 1.0, v33
	v_exp_f32_e32 v44, v44
	v_exp_f32_e32 v45, v45
	v_exp_f32_e32 v46, v46
	v_exp_f32_e32 v47, v47
	v_mul_f32_e32 v40, v40, v83
	v_mul_f32_e32 v41, v41, v83
	v_mul_f32_e32 v42, v42, v83
	v_mul_f32_e32 v43, v43, v83
	v_lshlrev_b32_e32 v68, 16, v73
	v_and_b32_e32 v69, 0xffff0000, v73
	v_rcp_f32_e32 v73, v32
	v_mul_f32_e32 v32, v34, v83
	v_exp_f32_e32 v40, v40
	v_exp_f32_e32 v41, v41
	v_exp_f32_e32 v42, v42
	v_exp_f32_e32 v43, v43
	v_mul_f32_e32 v36, v36, v83
	v_mul_f32_e32 v37, v37, v83
	v_mul_f32_e32 v38, v38, v83
	v_mul_f32_e32 v39, v39, v83
	v_exp_f32_e32 v32, v32
	v_mul_f32_e32 v33, v35, v83
	v_exp_f32_e32 v36, v36
	v_exp_f32_e32 v37, v37
	v_exp_f32_e32 v38, v38
	v_exp_f32_e32 v39, v39
	v_exp_f32_e32 v33, v33
	v_add_f32_e32 v44, 1.0, v44
	v_add_f32_e32 v45, 1.0, v45
	v_add_f32_e32 v46, 1.0, v46
	v_add_f32_e32 v47, 1.0, v47
	v_rcp_f32_e32 v44, v44
	v_rcp_f32_e32 v45, v45
	v_rcp_f32_e32 v46, v46
	v_rcp_f32_e32 v47, v47
	v_add_f32_e32 v40, 1.0, v40
	v_add_f32_e32 v41, 1.0, v41
	v_add_f32_e32 v42, 1.0, v42
	v_add_f32_e32 v43, 1.0, v43
	v_add_f32_e32 v32, 1.0, v32
	v_rcp_f32_e32 v40, v40
	v_rcp_f32_e32 v41, v41
	v_rcp_f32_e32 v42, v42
	v_rcp_f32_e32 v43, v43
	v_add_f32_e32 v36, 1.0, v36
	v_add_f32_e32 v37, 1.0, v37
	v_add_f32_e32 v38, 1.0, v38
	v_add_f32_e32 v39, 1.0, v39
	v_rcp_f32_e32 v84, v32
	v_add_f32_e32 v32, 1.0, v33
	v_rcp_f32_e32 v36, v36
	v_rcp_f32_e32 v37, v37
	v_rcp_f32_e32 v38, v38
	v_rcp_f32_e32 v39, v39
	v_rcp_f32_e32 v85, v32
	v_lshlrev_b64 v[32:33], 12, v[80:81]
	v_lshl_add_u64 v[32:33], s[84:85], 0, v[32:33]
	v_lshlrev_b32_e32 v56, 16, v66
	v_and_b32_e32 v57, 0xffff0000, v66
	v_lshlrev_b32_e32 v58, 16, v70
	v_and_b32_e32 v59, 0xffff0000, v70
	v_lshlrev_b32_e32 v60, 16, v67
	v_and_b32_e32 v61, 0xffff0000, v67
	v_lshlrev_b32_e32 v62, 16, v71
	v_and_b32_e32 v63, 0xffff0000, v71
	v_lshl_add_u64 v[80:81], v[32:33], 0, v[112:113]
	v_pk_fma_f32 v[218:219], v[46:47], v[52:53], v[54:55]
	v_pk_fma_f32 v[216:217], v[44:45], v[48:49], v[50:51]
	s_waitcnt vmcnt(0)
	v_lshlrev_b32_e32 v66, 16, v76
	v_and_b32_e32 v67, 0xffff0000, v76
	v_lshlrev_b32_e32 v70, 16, v77
	v_and_b32_e32 v71, 0xffff0000, v77
	v_lshlrev_b32_e32 v76, 16, v74
	v_and_b32_e32 v77, 0xffff0000, v74
	v_pk_fma_f32 v[222:223], v[42:43], v[60:61], v[62:63]
	v_pk_fma_f32 v[220:221], v[40:41], v[56:57], v[58:59]
	v_lshlrev_b32_e32 v82, 16, v78
	v_and_b32_e32 v83, 0xffff0000, v78
	v_lshlrev_b32_e32 v74, 16, v75
	v_and_b32_e32 v75, 0xffff0000, v75
	v_lshlrev_b32_e32 v78, 16, v79
	v_and_b32_e32 v79, 0xffff0000, v79
	s_nop 1
	v_pk_fma_f32 v[226:227], v[38:39], v[68:69], v[70:71]
	v_pk_fma_f32 v[224:225], v[36:37], v[64:65], v[66:67]
	v_add_u32_e32 v64, 0xa0, v140
	v_ashrrev_i32_e32 v65, 31, v64
	s_nop 0
	v_pk_fma_f32 v[230:231], v[84:85], v[74:75], v[78:79]
	v_pk_fma_f32 v[228:229], v[72:73], v[76:77], v[82:83]
	s_nop 1
	v_permlane16_swap_b32_e32 v216, v220
	v_permlane16_swap_b32_e32 v217, v221
	v_permlane16_swap_b32_e32 v218, v222
	v_permlane16_swap_b32_e32 v219, v223
	v_permlane16_swap_b32_e32 v224, v228
	v_permlane16_swap_b32_e32 v225, v229
	v_permlane16_swap_b32_e32 v226, v230
	v_permlane16_swap_b32_e32 v227, v231
	v_permlane32_swap_b32_e32 v216, v224
	v_permlane32_swap_b32_e32 v217, v225
	v_permlane32_swap_b32_e32 v218, v226
	v_permlane32_swap_b32_e32 v219, v227
	v_permlane32_swap_b32_e32 v220, v228
	v_permlane32_swap_b32_e32 v221, v229
	v_permlane32_swap_b32_e32 v222, v230
	v_permlane32_swap_b32_e32 v223, v231
	v_lshl_add_u64 v[234:235], v[80:81], 0, v[232:233]
	global_store_dwordx4 v[234:235], v[216:219], off
	global_store_dwordx4 v[234:235], v[220:223], off offset:64
	global_store_dwordx4 v[234:235], v[224:227], off offset:128
	global_store_dwordx4 v[234:235], v[228:231], off offset:192
	s_nop 1
	v_lshlrev_b64 v[32:33], 6, v[64:65]
	v_lshl_add_u64 v[48:49], s[6:7], 0, v[32:33]
	v_lshlrev_b64 v[48:49], 11, v[64:65]
	v_lshl_add_u64 v[50:51], s[8:9], 0, v[48:49]
	v_lshl_add_u64 v[66:67], v[50:51], 0, v[138:139]
	v_lshl_add_u64 v[52:53], s[0:1], 0, v[48:49]
	global_load_dwordx4 v[48:51], v[66:67], off
	v_lshl_add_u64 v[68:69], v[52:53], 0, v[138:139]
	global_load_dwordx4 v[52:55], v[68:69], off
	global_load_dwordx4 v[56:59], v[66:67], off offset:16
	global_load_dwordx4 v[60:63], v[68:69], off offset:16
	s_waitcnt vmcnt(7)
	s_waitcnt vmcnt(6)
	s_waitcnt vmcnt(5)
	s_waitcnt vmcnt(4)
	s_waitcnt vmcnt(3)
	v_lshlrev_b32_e32 v36, 16, v49
	v_and_b32_e32 v37, 0xffff0000, v49
	v_fmamk_f32 v32, v214, 0x3a800000, v150
	v_mul_f32_e32 v33, 0x4b800000, v32
	v_cmp_gt_f32_e32 vcc, s51, v32
	s_waitcnt vmcnt(1)
	v_and_b32_e32 v49, 0xffff0000, v56
	v_lshlrev_b32_e32 v34, 16, v52
	v_cndmask_b32_e32 v32, v32, v33, vcc
	v_rsq_f32_e32 v32, v32
	v_and_b32_e32 v35, 0xffff0000, v52
	v_lshlrev_b32_e32 v38, 16, v53
	v_and_b32_e32 v39, 0xffff0000, v53
	v_mul_f32_e32 v33, 0x45800000, v32
	v_cndmask_b32_e32 v32, v32, v33, vcc
	v_mul_f32_e32 v67, 0xbfb8aa3b, v32
	v_mul_f32_e32 v16, v16, v67
	v_exp_f32_e32 v16, v16
	v_mul_f32_e32 v17, v17, v67
	v_exp_f32_e32 v17, v17
	v_mul_f32_e32 v28, v28, v67
	v_add_f32_e32 v16, 1.0, v16
	v_mul_f32_e32 v29, v29, v67
	v_lshlrev_b32_e32 v32, 16, v48
	v_and_b32_e32 v33, 0xffff0000, v48
	v_mul_f32_e32 v30, v30, v67
	v_mul_f32_e32 v31, v31, v67
	v_lshlrev_b32_e32 v48, 16, v56
	v_rcp_f32_e32 v56, v16
	v_add_f32_e32 v16, 1.0, v17
	v_exp_f32_e32 v28, v28
	v_exp_f32_e32 v29, v29
	v_exp_f32_e32 v30, v30
	v_exp_f32_e32 v31, v31
	v_mul_f32_e32 v24, v24, v67
	v_mul_f32_e32 v25, v25, v67
	v_mul_f32_e32 v26, v26, v67
	v_mul_f32_e32 v27, v27, v67
	v_lshlrev_b32_e32 v52, 16, v57
	v_and_b32_e32 v53, 0xffff0000, v57
	v_rcp_f32_e32 v57, v16
	v_mul_f32_e32 v16, v18, v67
	v_exp_f32_e32 v24, v24
	v_exp_f32_e32 v25, v25
	v_exp_f32_e32 v26, v26
	v_exp_f32_e32 v27, v27
	v_mul_f32_e32 v20, v20, v67
	v_mul_f32_e32 v21, v21, v67
	v_mul_f32_e32 v22, v22, v67
	v_mul_f32_e32 v23, v23, v67
	v_exp_f32_e32 v16, v16
	v_mul_f32_e32 v17, v19, v67
	v_exp_f32_e32 v20, v20
	v_exp_f32_e32 v21, v21
	v_exp_f32_e32 v22, v22
	v_exp_f32_e32 v23, v23
	v_exp_f32_e32 v17, v17
	v_add_f32_e32 v28, 1.0, v28
	v_add_f32_e32 v29, 1.0, v29
	v_add_f32_e32 v30, 1.0, v30
	v_add_f32_e32 v31, 1.0, v31
	v_rcp_f32_e32 v28, v28
	v_rcp_f32_e32 v29, v29
	v_rcp_f32_e32 v30, v30
	v_rcp_f32_e32 v31, v31
	v_add_f32_e32 v24, 1.0, v24
	v_add_f32_e32 v25, 1.0, v25
	v_add_f32_e32 v26, 1.0, v26
	v_add_f32_e32 v27, 1.0, v27
	v_add_f32_e32 v16, 1.0, v16
	v_rcp_f32_e32 v24, v24
	v_rcp_f32_e32 v25, v25
	v_rcp_f32_e32 v26, v26
	v_rcp_f32_e32 v27, v27
	v_add_f32_e32 v20, 1.0, v20
	v_add_f32_e32 v21, 1.0, v21
	v_add_f32_e32 v22, 1.0, v22
	v_add_f32_e32 v23, 1.0, v23
	v_rcp_f32_e32 v68, v16
	v_add_f32_e32 v16, 1.0, v17
	v_rcp_f32_e32 v20, v20
	v_rcp_f32_e32 v21, v21
	v_rcp_f32_e32 v22, v22
	v_rcp_f32_e32 v23, v23
	v_rcp_f32_e32 v69, v16
	v_lshlrev_b64 v[16:17], 12, v[64:65]
	v_lshl_add_u64 v[16:17], s[84:85], 0, v[16:17]
	v_lshlrev_b32_e32 v40, 16, v50
	v_and_b32_e32 v41, 0xffff0000, v50
	v_lshlrev_b32_e32 v42, 16, v54
	v_and_b32_e32 v43, 0xffff0000, v54
	v_lshlrev_b32_e32 v44, 16, v51
	v_and_b32_e32 v45, 0xffff0000, v51
	v_lshlrev_b32_e32 v46, 16, v55
	v_and_b32_e32 v47, 0xffff0000, v55
	v_lshl_add_u64 v[64:65], v[16:17], 0, v[112:113]
	v_pk_fma_f32 v[218:219], v[30:31], v[36:37], v[38:39]
	v_pk_fma_f32 v[216:217], v[28:29], v[32:33], v[34:35]
	s_waitcnt vmcnt(0)
	v_lshlrev_b32_e32 v50, 16, v60
	v_and_b32_e32 v51, 0xffff0000, v60
	v_lshlrev_b32_e32 v54, 16, v61
	v_and_b32_e32 v55, 0xffff0000, v61
	v_lshlrev_b32_e32 v60, 16, v58
	v_and_b32_e32 v61, 0xffff0000, v58
	v_pk_fma_f32 v[222:223], v[26:27], v[44:45], v[46:47]
	v_pk_fma_f32 v[220:221], v[24:25], v[40:41], v[42:43]
	v_lshlrev_b32_e32 v66, 16, v62
	v_and_b32_e32 v67, 0xffff0000, v62
	v_lshlrev_b32_e32 v58, 16, v59
	v_and_b32_e32 v59, 0xffff0000, v59
	v_lshlrev_b32_e32 v62, 16, v63
	v_and_b32_e32 v63, 0xffff0000, v63
	s_nop 1
	v_pk_fma_f32 v[226:227], v[22:23], v[52:53], v[54:55]
	v_pk_fma_f32 v[224:225], v[20:21], v[48:49], v[50:51]
	v_add_u32_e32 v48, 0xb0, v140
	v_ashrrev_i32_e32 v49, 31, v48
	s_nop 0
	v_pk_fma_f32 v[230:231], v[68:69], v[58:59], v[62:63]
	v_pk_fma_f32 v[228:229], v[56:57], v[60:61], v[66:67]
	s_nop 1
	v_permlane16_swap_b32_e32 v216, v220
	v_permlane16_swap_b32_e32 v217, v221
	v_permlane16_swap_b32_e32 v218, v222
	v_permlane16_swap_b32_e32 v219, v223
	v_permlane16_swap_b32_e32 v224, v228
	v_permlane16_swap_b32_e32 v225, v229
	v_permlane16_swap_b32_e32 v226, v230
	v_permlane16_swap_b32_e32 v227, v231
	v_permlane32_swap_b32_e32 v216, v224
	v_permlane32_swap_b32_e32 v217, v225
	v_permlane32_swap_b32_e32 v218, v226
	v_permlane32_swap_b32_e32 v219, v227
	v_permlane32_swap_b32_e32 v220, v228
	v_permlane32_swap_b32_e32 v221, v229
	v_permlane32_swap_b32_e32 v222, v230
	v_permlane32_swap_b32_e32 v223, v231
	v_lshl_add_u64 v[234:235], v[64:65], 0, v[232:233]
	global_store_dwordx4 v[234:235], v[216:219], off
	global_store_dwordx4 v[234:235], v[220:223], off offset:64
	global_store_dwordx4 v[234:235], v[224:227], off offset:128
	global_store_dwordx4 v[234:235], v[228:231], off offset:192
	s_nop 1
	v_lshlrev_b64 v[16:17], 6, v[48:49]
	v_lshl_add_u64 v[32:33], s[6:7], 0, v[16:17]
	v_lshlrev_b64 v[32:33], 11, v[48:49]
	v_lshl_add_u64 v[34:35], s[8:9], 0, v[32:33]
	v_lshl_add_u64 v[50:51], v[34:35], 0, v[138:139]
	v_lshl_add_u64 v[36:37], s[0:1], 0, v[32:33]
	global_load_dwordx4 v[32:35], v[50:51], off
	v_lshl_add_u64 v[52:53], v[36:37], 0, v[138:139]
	global_load_dwordx4 v[36:39], v[52:53], off
	global_load_dwordx4 v[40:43], v[50:51], off offset:16
	global_load_dwordx4 v[44:47], v[52:53], off offset:16
	s_waitcnt vmcnt(7)
	s_waitcnt vmcnt(6)
	s_waitcnt vmcnt(5)
	s_waitcnt vmcnt(4)
	s_waitcnt vmcnt(3)
	v_lshlrev_b32_e32 v20, 16, v33
	v_and_b32_e32 v21, 0xffff0000, v33
	v_fmamk_f32 v16, v215, 0x3a800000, v150
	v_mul_f32_e32 v17, 0x4b800000, v16
	v_cmp_gt_f32_e32 vcc, s51, v16
	s_waitcnt vmcnt(1)
	v_and_b32_e32 v33, 0xffff0000, v40
	v_lshlrev_b32_e32 v18, 16, v36
	v_cndmask_b32_e32 v16, v16, v17, vcc
	v_rsq_f32_e32 v16, v16
	v_and_b32_e32 v19, 0xffff0000, v36
	v_lshlrev_b32_e32 v22, 16, v37
	v_and_b32_e32 v23, 0xffff0000, v37
	v_mul_f32_e32 v17, 0x45800000, v16
	v_cndmask_b32_e32 v16, v16, v17, vcc
	v_mul_f32_e32 v51, 0xbfb8aa3b, v16
	v_mul_f32_e32 v0, v0, v51
	v_exp_f32_e32 v0, v0
	v_mul_f32_e32 v1, v1, v51
	v_exp_f32_e32 v1, v1
	v_mul_f32_e32 v12, v12, v51
	v_add_f32_e32 v0, 1.0, v0
	v_mul_f32_e32 v13, v13, v51
	v_lshlrev_b32_e32 v16, 16, v32
	v_and_b32_e32 v17, 0xffff0000, v32
	v_mul_f32_e32 v14, v14, v51
	v_mul_f32_e32 v15, v15, v51
	v_lshlrev_b32_e32 v32, 16, v40
	v_rcp_f32_e32 v40, v0
	v_add_f32_e32 v0, 1.0, v1
	v_exp_f32_e32 v12, v12
	v_exp_f32_e32 v13, v13
	v_exp_f32_e32 v14, v14
	v_exp_f32_e32 v15, v15
	v_mul_f32_e32 v8, v8, v51
	v_mul_f32_e32 v9, v9, v51
	v_mul_f32_e32 v10, v10, v51
	v_mul_f32_e32 v11, v11, v51
	v_lshlrev_b32_e32 v36, 16, v41
	v_and_b32_e32 v37, 0xffff0000, v41
	v_rcp_f32_e32 v41, v0
	v_mul_f32_e32 v0, v2, v51
	v_exp_f32_e32 v8, v8
	v_exp_f32_e32 v9, v9
	v_exp_f32_e32 v10, v10
	v_exp_f32_e32 v11, v11
	v_mul_f32_e32 v4, v4, v51
	v_mul_f32_e32 v5, v5, v51
	v_mul_f32_e32 v6, v6, v51
	v_mul_f32_e32 v7, v7, v51
	v_exp_f32_e32 v0, v0
	v_mul_f32_e32 v1, v3, v51
	v_exp_f32_e32 v4, v4
	v_exp_f32_e32 v5, v5
	v_exp_f32_e32 v6, v6
	v_exp_f32_e32 v7, v7
	v_exp_f32_e32 v1, v1
	v_add_f32_e32 v12, 1.0, v12
	v_add_f32_e32 v13, 1.0, v13
	v_add_f32_e32 v14, 1.0, v14
	v_add_f32_e32 v15, 1.0, v15
	v_rcp_f32_e32 v12, v12
	v_rcp_f32_e32 v13, v13
	v_rcp_f32_e32 v14, v14
	v_rcp_f32_e32 v15, v15
	v_add_f32_e32 v8, 1.0, v8
	v_add_f32_e32 v9, 1.0, v9
	v_add_f32_e32 v10, 1.0, v10
	v_add_f32_e32 v11, 1.0, v11
	v_add_f32_e32 v0, 1.0, v0
	v_rcp_f32_e32 v8, v8
	v_rcp_f32_e32 v9, v9
	v_rcp_f32_e32 v10, v10
	v_rcp_f32_e32 v11, v11
	v_add_f32_e32 v4, 1.0, v4
	v_add_f32_e32 v5, 1.0, v5
	v_add_f32_e32 v6, 1.0, v6
	v_add_f32_e32 v7, 1.0, v7
	v_rcp_f32_e32 v52, v0
	v_add_f32_e32 v0, 1.0, v1
	v_rcp_f32_e32 v4, v4
	v_rcp_f32_e32 v5, v5
	v_rcp_f32_e32 v6, v6
	v_rcp_f32_e32 v7, v7
	v_rcp_f32_e32 v53, v0
	v_lshlrev_b64 v[0:1], 12, v[48:49]
	v_lshl_add_u64 v[0:1], s[84:85], 0, v[0:1]
	v_lshlrev_b32_e32 v24, 16, v34
	v_and_b32_e32 v25, 0xffff0000, v34
	v_lshlrev_b32_e32 v26, 16, v38
	v_and_b32_e32 v27, 0xffff0000, v38
	v_lshlrev_b32_e32 v28, 16, v35
	v_and_b32_e32 v29, 0xffff0000, v35
	v_lshlrev_b32_e32 v30, 16, v39
	v_and_b32_e32 v31, 0xffff0000, v39
	v_lshl_add_u64 v[48:49], v[0:1], 0, v[112:113]
	v_pk_fma_f32 v[218:219], v[14:15], v[20:21], v[22:23]
	v_pk_fma_f32 v[216:217], v[12:13], v[16:17], v[18:19]
	s_waitcnt vmcnt(0)
	v_lshlrev_b32_e32 v34, 16, v44
	v_and_b32_e32 v35, 0xffff0000, v44
	v_lshlrev_b32_e32 v38, 16, v45
	v_and_b32_e32 v39, 0xffff0000, v45
	v_lshlrev_b32_e32 v44, 16, v42
	v_and_b32_e32 v45, 0xffff0000, v42
	v_pk_fma_f32 v[222:223], v[10:11], v[28:29], v[30:31]
	v_pk_fma_f32 v[220:221], v[8:9], v[24:25], v[26:27]
	v_lshlrev_b32_e32 v50, 16, v46
	v_and_b32_e32 v51, 0xffff0000, v46
	v_lshlrev_b32_e32 v42, 16, v43
	v_and_b32_e32 v43, 0xffff0000, v43
	v_lshlrev_b32_e32 v46, 16, v47
	v_and_b32_e32 v47, 0xffff0000, v47
	s_nop 1
	v_pk_fma_f32 v[226:227], v[6:7], v[36:37], v[38:39]
	v_pk_fma_f32 v[224:225], v[4:5], v[32:33], v[34:35]
	s_nop 1
	v_pk_fma_f32 v[230:231], v[52:53], v[42:43], v[46:47]
	v_pk_fma_f32 v[228:229], v[40:41], v[44:45], v[50:51]
	s_nop 1
	v_permlane16_swap_b32_e32 v216, v220
	v_permlane16_swap_b32_e32 v217, v221
	v_permlane16_swap_b32_e32 v218, v222
	v_permlane16_swap_b32_e32 v219, v223
	v_permlane16_swap_b32_e32 v224, v228
	v_permlane16_swap_b32_e32 v225, v229
	v_permlane16_swap_b32_e32 v226, v230
	v_permlane16_swap_b32_e32 v227, v231
	v_permlane32_swap_b32_e32 v216, v224
	v_permlane32_swap_b32_e32 v217, v225
	v_permlane32_swap_b32_e32 v218, v226
	v_permlane32_swap_b32_e32 v219, v227
	v_permlane32_swap_b32_e32 v220, v228
	v_permlane32_swap_b32_e32 v221, v229
	v_permlane32_swap_b32_e32 v222, v230
	v_permlane32_swap_b32_e32 v223, v231
	v_lshl_add_u64 v[234:235], v[48:49], 0, v[232:233]
	global_store_dwordx4 v[234:235], v[216:219], off
	global_store_dwordx4 v[234:235], v[220:223], off offset:64
	global_store_dwordx4 v[234:235], v[224:227], off offset:128
	global_store_dwordx4 v[234:235], v[228:231], off offset:192
	s_cbranch_scc1 .LBB0_1643
	s_andn2_b64 vcc, exec, s[4:5]
	s_cbranch_vccnz .LBB0_1642
	s_barrier
	s_branch .LBB0_1642
